# GEMM K-loops: LDS-DMA stages use the SGPR-base address form (16 VALU 64-bit adds per K-iteration replaced by 4 SALU)
# speedup vs baseline: 1.0452x; 1.0032x over previous
; #define PG8_STAGE(bufoff, gbase, voff) do { _Pragma("unroll") for (int _i = 0; _i < 2; ++_i) \
;         __builtin_amdgcn_global_load_lds((const unsigned*)((const char*)(gbase) + (voff)[_i]), (PG8_LAS unsigned*)(lds + (bufoff) + ldsw + _i * 8192), 16, 0, 0); } while (0)
; #define PG8_LDA(dst, b, h) do { _Pragma("unroll") for (int m = 0; m < 4; ++m) _Pragma("unroll") for (int k = 0; k < 2; ++k) dst[m][k] = *(const PG8_LAS bf16x8*)(lds + PG8_SA(b, h) + aoff + m * 2048 + k * 1024); } while (0)
; #define PG8_LDB(dst, b, h) do { _Pragma("unroll") for (int n = 0; n < 2; ++n) _Pragma("unroll") for (int k = 0; k < 2; ++k) dst[n][k] = *(const PG8_LAS bf16x8*)(lds + PG8_SB(b, h) + boff + n * 2048 + k * 1024); } while (0)
; #define PG8_MMA(ai, bj, At, Bt) do { __builtin_amdgcn_s_setprio(1); _Pragma("unroll") for (int m = 0; m < 4; ++m) _Pragma("unroll") for (int n = 0; n < 2; ++n) _Pragma("unroll") for (int k = 0; k < 2; ++k) \
;         acc[ai][bj][m][n] = __builtin_amdgcn_mfma_f32_16x16x32_bf16(Bt[n][k], At[m][k], acc[ai][bj][m][n], 0, 0, 0); __builtin_amdgcn_s_setprio(0); } while (0)
; #define PG8_WAIT_V(n) asm volatile("s_waitcnt vmcnt(" #n ")" ::: "memory")
; template <class Epi, class Sched>
; __device__ __forceinline__ void gemm_phase(PG8_LAS unsigned char* lds, const Gemm g, const Sched& S, const Epi& E) {
;     ...
;         for (int t = 0; t < nt; t += 2) {
;             const bool last = (t == nt - 2);
;             const char* a1 = cA + (size_t)(t + 1) * kstep;
;             const char* a2 = last ? nA : cA + (size_t)(t + 2) * kstep; const char* b2 = last ? nB : cB + (size_t)(t + 2) * kstep;
;             const char* a3 = a2 + kstep; const char* b3 = b2 + kstep;
;             if (last && has_next) S.a_ready(nxt);
;             PG8_LDB(B0, 0, 0); PG8_SCHED; PG8_LDA(At, 0, 0); PG8_STAGE(PG8_SA(1, 1), a1 + hstep, voffA);
;             PG8_WAIT_L(8); PG8_BAR; PG8_WAIT_L(0); PG8_MMA(0, 0, At, B0); PG8_BAR; PG8_SCHED;
;             PG8_LDB(B1, 0, 1); PG8_STAGE(PG8_SB(0, 0), b2, voffB);
;             PG8_BAR; PG8_WAIT_L(0); PG8_MMA(0, 1, At, B1); PG8_BAR;
;             PG8_LDA(At, 0, 1); PG8_STAGE(PG8_SA(0, 0), a2, voffA);
;             PG8_BAR; PG8_WAIT_L(0); PG8_MMA(1, 0, At, B0); PG8_BAR; PG8_SCHED;
;             PG8_STAGE(PG8_SB(0, 1), b2 + hstep, voffB);
;             PG8_WAIT_V(6); PG8_BAR; PG8_MMA(1, 1, At, B1); PG8_BAR;
.LBB0_96:
	s_add_u32 s10, s8, 0x100
	s_addc_u32 s11, s9, 0
	s_add_i32 s46, 0, 0x10000
	v_add_u32_e32 v154, s46, v139
	ds_read_b128 v[142:145], v154
	ds_read_b128 v[146:149], v154 offset:1024
	ds_read_b128 v[150:153], v154 offset:2048
	ds_read_b128 v[154:157], v154 offset:3072
	s_cmp_eq_u32 s45, 40
	s_cselect_b32 s15, s1, s11
	s_cselect_b32 s14, s0, s10
	s_cselect_b32 s13, s5, s44
	s_cselect_b32 s12, s4, s43
	s_add_i32 m0, s20, 0xc000
	ds_read_b128 v[158:161], v141
	ds_read_b128 v[162:165], v141 offset:1024
	ds_read_b128 v[166:169], v141 offset:2048
	ds_read_b128 v[170:173], v141 offset:3072
	ds_read_b128 v[178:181], v141 offset:4096
	ds_read_b128 v[182:185], v141 offset:5120
	ds_read_b128 v[186:189], v141 offset:6144
	ds_read_b128 v[190:193], v141 offset:7168
	global_load_lds_dwordx4 v134, s[8:9]
	s_add_i32 m0, s20, 0xe000
	s_nop 0
	global_load_lds_dwordx4 v136, s[8:9]
	s_waitcnt lgkmcnt(8)
	s_barrier
	s_waitcnt lgkmcnt(0)
	s_setprio 1
	v_mfma_f32_16x16x32_bf16 v[124:127], v[142:145], v[158:161], v[124:127]
	v_mfma_f32_16x16x32_bf16 v[120:123], v[150:153], v[158:161], v[120:123]
	v_mfma_f32_16x16x32_bf16 v[116:119], v[142:145], v[166:169], v[116:119]
	v_mfma_f32_16x16x32_bf16 v[112:115], v[150:153], v[166:169], v[112:115]
	v_mfma_f32_16x16x32_bf16 v[100:103], v[142:145], v[178:181], v[100:103]
	v_mfma_f32_16x16x32_bf16 v[96:99], v[150:153], v[178:181], v[96:99]
	v_mfma_f32_16x16x32_bf16 v[84:87], v[142:145], v[186:189], v[84:87]
	v_mfma_f32_16x16x32_bf16 v[80:83], v[150:153], v[186:189], v[80:83]
	v_mfma_f32_16x16x32_bf16 v[124:127], v[146:149], v[162:165], v[124:127]
	v_mfma_f32_16x16x32_bf16 v[120:123], v[154:157], v[162:165], v[120:123]
	v_mfma_f32_16x16x32_bf16 v[116:119], v[146:149], v[170:173], v[116:119]
	v_mfma_f32_16x16x32_bf16 v[112:115], v[154:157], v[170:173], v[112:115]
	v_mfma_f32_16x16x32_bf16 v[100:103], v[146:149], v[182:185], v[100:103]
	v_mfma_f32_16x16x32_bf16 v[96:99], v[154:157], v[182:185], v[96:99]
	v_mfma_f32_16x16x32_bf16 v[84:87], v[146:149], v[190:193], v[84:87]
	v_mfma_f32_16x16x32_bf16 v[80:83], v[154:157], v[190:193], v[80:83]
	s_setprio 0
	s_barrier
	s_add_i32 s47, 0, 0x14000
	v_add_u32_e32 v174, s47, v139
	s_add_i32 s8, s46, s18
	ds_read_b128 v[194:197], v174
	ds_read_b128 v[198:201], v174 offset:1024
	ds_read_b128 v[202:205], v174 offset:2048
	ds_read_b128 v[206:209], v174 offset:3072
	s_add_u32 s98, s12, 0x80
	s_addc_u32 s99, s13, 0
	s_mov_b32 m0, s8
	s_nop 0
	global_load_lds_dwordx4 v176, s[12:13]
	s_add_i32 m0, s8, 0x2000
	s_nop 0
	global_load_lds_dwordx4 v128, s[12:13]
	s_barrier
	s_waitcnt lgkmcnt(0)
	s_setprio 1
	v_mfma_f32_16x16x32_bf16 v[108:111], v[194:197], v[158:161], v[108:111]
	v_mfma_f32_16x16x32_bf16 v[104:107], v[202:205], v[158:161], v[104:107]
	v_mfma_f32_16x16x32_bf16 v[92:95], v[194:197], v[166:169], v[92:95]
	v_mfma_f32_16x16x32_bf16 v[88:91], v[202:205], v[166:169], v[88:91]
	v_mfma_f32_16x16x32_bf16 v[76:79], v[194:197], v[178:181], v[76:79]
	v_mfma_f32_16x16x32_bf16 v[72:75], v[202:205], v[178:181], v[72:75]
	v_mfma_f32_16x16x32_bf16 v[68:71], v[194:197], v[186:189], v[68:71]
	v_mfma_f32_16x16x32_bf16 v[64:67], v[202:205], v[186:189], v[64:67]
	v_mfma_f32_16x16x32_bf16 v[108:111], v[198:201], v[162:165], v[108:111]
	v_mfma_f32_16x16x32_bf16 v[104:107], v[206:209], v[162:165], v[104:107]
	v_mfma_f32_16x16x32_bf16 v[92:95], v[198:201], v[170:173], v[92:95]
	v_mfma_f32_16x16x32_bf16 v[88:91], v[206:209], v[170:173], v[88:91]
	v_mfma_f32_16x16x32_bf16 v[76:79], v[198:201], v[182:185], v[76:79]
	v_mfma_f32_16x16x32_bf16 v[72:75], v[206:209], v[182:185], v[72:75]
	v_mfma_f32_16x16x32_bf16 v[68:71], v[198:201], v[190:193], v[68:71]
	v_mfma_f32_16x16x32_bf16 v[64:67], v[206:209], v[190:193], v[64:67]
	s_setprio 0
	s_mov_b32 m0, s20
	s_add_u32 s100, s14, 0x80
	s_addc_u32 s101, s15, 0
	s_barrier
	ds_read_b128 v[158:161], v141 offset:16384
	ds_read_b128 v[162:165], v141 offset:17408
	ds_read_b128 v[166:169], v141 offset:18432
	ds_read_b128 v[170:173], v141 offset:19456
	ds_read_b128 v[178:181], v141 offset:20480
	ds_read_b128 v[182:185], v141 offset:21504
	ds_read_b128 v[186:189], v141 offset:22528
	ds_read_b128 v[190:193], v141 offset:23552
	global_load_lds_dwordx4 v132, s[14:15]
	s_mov_b32 m0, s21
	s_nop 0
	global_load_lds_dwordx4 v130, s[14:15]
	s_barrier
	s_waitcnt lgkmcnt(0)
	s_setprio 1
	v_mfma_f32_16x16x32_bf16 v[60:63], v[142:145], v[158:161], v[60:63]
	v_mfma_f32_16x16x32_bf16 v[56:59], v[150:153], v[158:161], v[56:59]
	v_mfma_f32_16x16x32_bf16 v[52:55], v[142:145], v[166:169], v[52:55]
	v_mfma_f32_16x16x32_bf16 v[48:51], v[150:153], v[166:169], v[48:51]
	v_mfma_f32_16x16x32_bf16 v[36:39], v[142:145], v[178:181], v[36:39]
	v_mfma_f32_16x16x32_bf16 v[32:35], v[150:153], v[178:181], v[32:35]
	v_mfma_f32_16x16x32_bf16 v[20:23], v[142:145], v[186:189], v[20:23]
	v_mfma_f32_16x16x32_bf16 v[16:19], v[150:153], v[186:189], v[16:19]
	v_mfma_f32_16x16x32_bf16 v[60:63], v[146:149], v[162:165], v[60:63]
	v_mfma_f32_16x16x32_bf16 v[56:59], v[154:157], v[162:165], v[56:59]
	v_mfma_f32_16x16x32_bf16 v[52:55], v[146:149], v[170:173], v[52:55]
	v_mfma_f32_16x16x32_bf16 v[48:51], v[154:157], v[170:173], v[48:51]
	v_mfma_f32_16x16x32_bf16 v[36:39], v[146:149], v[182:185], v[36:39]
	v_mfma_f32_16x16x32_bf16 v[32:35], v[154:157], v[182:185], v[32:35]
	v_mfma_f32_16x16x32_bf16 v[20:23], v[146:149], v[190:193], v[20:23]
	v_mfma_f32_16x16x32_bf16 v[16:19], v[154:157], v[190:193], v[16:19]
	s_setprio 0
	s_barrier
	s_add_u32 s8, s12, 0xb0000
	s_addc_u32 s9, s13, 0
	s_add_i32 s46, s47, s18
	s_mov_b32 m0, s46
	s_nop 0
	global_load_lds_dwordx4 v176, s[8:9]
	s_add_i32 m0, s46, 0x2000
	s_nop 0
	global_load_lds_dwordx4 v128, s[8:9]
	s_waitcnt vmcnt(6)
	s_barrier
; #define PG8_STAGE(bufoff, gbase, voff) do { _Pragma("unroll") for (int _i = 0; _i < 2; ++_i) \
;         __builtin_amdgcn_global_load_lds((const unsigned*)((const char*)(gbase) + (voff)[_i]), (PG8_LAS unsigned*)(lds + (bufoff) + ldsw + _i * 8192), 16, 0, 0); } while (0)
; #define PG8_LDA(dst, b, h) do { _Pragma("unroll") for (int m = 0; m < 4; ++m) _Pragma("unroll") for (int k = 0; k < 2; ++k) dst[m][k] = *(const PG8_LAS bf16x8*)(lds + PG8_SA(b, h) + aoff + m * 2048 + k * 1024); } while (0)
; #define PG8_LDB(dst, b, h) do { _Pragma("unroll") for (int n = 0; n < 2; ++n) _Pragma("unroll") for (int k = 0; k < 2; ++k) dst[n][k] = *(const PG8_LAS bf16x8*)(lds + PG8_SB(b, h) + boff + n * 2048 + k * 1024); } while (0)
; #define PG8_MMA(ai, bj, At, Bt) do { __builtin_amdgcn_s_setprio(1); _Pragma("unroll") for (int m = 0; m < 4; ++m) _Pragma("unroll") for (int n = 0; n < 2; ++n) _Pragma("unroll") for (int k = 0; k < 2; ++k) \
;         acc[ai][bj][m][n] = __builtin_amdgcn_mfma_f32_16x16x32_bf16(Bt[n][k], At[m][k], acc[ai][bj][m][n], 0, 0, 0); __builtin_amdgcn_s_setprio(0); } while (0)
; #define PG8_WAIT_V(n) asm volatile("s_waitcnt vmcnt(" #n ")" ::: "memory")
; #define PG8_WAIT_L(n) asm volatile("s_waitcnt lgkmcnt(" #n ")" ::: "memory")
; #define PG8_BAR __builtin_amdgcn_s_barrier()
; #define PG8_SCHED __builtin_amdgcn_sched_barrier(0)
; template <class Epi, class Sched>
; __device__ __forceinline__ void gemm_phase(PG8_LAS unsigned char* lds, const Gemm g, const Sched& S, const Epi& E) {
;     ...
;             PG8_WAIT_V(6); PG8_BAR; PG8_MMA(1, 1, At, B1); PG8_BAR;
;             PG8_LDB(B0, 1, 0); PG8_SCHED; PG8_LDA(At, 1, 0); PG8_STAGE(PG8_SA(0, 1), a2 + hstep, voffA);
;             PG8_WAIT_L(8); PG8_BAR; PG8_WAIT_L(0); PG8_MMA(0, 0, At, B0); PG8_BAR; PG8_SCHED;
;             PG8_LDB(B1, 1, 1); PG8_STAGE(PG8_SB(1, 0), b3, voffB);
;             PG8_BAR; PG8_WAIT_L(0); PG8_MMA(0, 1, At, B1); PG8_BAR;
;             PG8_LDA(At, 1, 1); PG8_STAGE(PG8_SA(1, 0), a3, voffA);
	s_setprio 1
	v_mfma_f32_16x16x32_bf16 v[44:47], v[194:197], v[158:161], v[44:47]
	v_mfma_f32_16x16x32_bf16 v[40:43], v[202:205], v[158:161], v[40:43]
	v_mfma_f32_16x16x32_bf16 v[28:31], v[194:197], v[166:169], v[28:31]
	v_mfma_f32_16x16x32_bf16 v[24:27], v[202:205], v[166:169], v[24:27]
	v_mfma_f32_16x16x32_bf16 v[12:15], v[194:197], v[178:181], v[12:15]
	v_mfma_f32_16x16x32_bf16 v[8:11], v[202:205], v[178:181], v[8:11]
	v_mfma_f32_16x16x32_bf16 v[4:7], v[194:197], v[186:189], v[4:7]
	v_mfma_f32_16x16x32_bf16 v[0:3], v[202:205], v[186:189], v[0:3]
	v_mfma_f32_16x16x32_bf16 v[44:47], v[198:201], v[162:165], v[44:47]
	v_mfma_f32_16x16x32_bf16 v[40:43], v[206:209], v[162:165], v[40:43]
	v_mfma_f32_16x16x32_bf16 v[28:31], v[198:201], v[170:173], v[28:31]
	v_mfma_f32_16x16x32_bf16 v[24:27], v[206:209], v[170:173], v[24:27]
	v_mfma_f32_16x16x32_bf16 v[12:15], v[198:201], v[182:185], v[12:15]
	v_mfma_f32_16x16x32_bf16 v[8:11], v[206:209], v[182:185], v[8:11]
	v_mfma_f32_16x16x32_bf16 v[4:7], v[198:201], v[190:193], v[4:7]
	v_mfma_f32_16x16x32_bf16 v[0:3], v[206:209], v[190:193], v[0:3]
	s_setprio 0
	s_add_i32 s46, 0, 0x18000
	v_add_u32_e32 v154, s46, v139
	s_barrier
	ds_read_b128 v[142:145], v154
	ds_read_b128 v[146:149], v154 offset:1024
	ds_read_b128 v[150:153], v154 offset:2048
	ds_read_b128 v[154:157], v154 offset:3072
	s_add_u32 s8, s14, 0xb0000
	s_addc_u32 s9, s15, 0
	s_mov_b32 m0, s22
	ds_read_b128 v[158:161], v141 offset:32768
	ds_read_b128 v[162:165], v141 offset:33792
	ds_read_b128 v[166:169], v141 offset:34816
	ds_read_b128 v[170:173], v141 offset:35840
	ds_read_b128 v[178:181], v141 offset:36864
	ds_read_b128 v[182:185], v141 offset:37888
	ds_read_b128 v[186:189], v141 offset:38912
	ds_read_b128 v[190:193], v141 offset:39936
	global_load_lds_dwordx4 v132, s[8:9]
	s_mov_b32 m0, s23
	s_nop 0
	global_load_lds_dwordx4 v130, s[8:9]
	s_waitcnt lgkmcnt(8)
	s_barrier
	s_waitcnt lgkmcnt(0)
	s_setprio 1
	v_mfma_f32_16x16x32_bf16 v[124:127], v[142:145], v[158:161], v[124:127]
	v_mfma_f32_16x16x32_bf16 v[120:123], v[150:153], v[158:161], v[120:123]
	v_mfma_f32_16x16x32_bf16 v[116:119], v[142:145], v[166:169], v[116:119]
	v_mfma_f32_16x16x32_bf16 v[112:115], v[150:153], v[166:169], v[112:115]
	v_mfma_f32_16x16x32_bf16 v[100:103], v[142:145], v[178:181], v[100:103]
	v_mfma_f32_16x16x32_bf16 v[96:99], v[150:153], v[178:181], v[96:99]
	v_mfma_f32_16x16x32_bf16 v[84:87], v[142:145], v[186:189], v[84:87]
	v_mfma_f32_16x16x32_bf16 v[80:83], v[150:153], v[186:189], v[80:83]
	v_mfma_f32_16x16x32_bf16 v[124:127], v[146:149], v[162:165], v[124:127]
	v_mfma_f32_16x16x32_bf16 v[120:123], v[154:157], v[162:165], v[120:123]
	v_mfma_f32_16x16x32_bf16 v[116:119], v[146:149], v[170:173], v[116:119]
	v_mfma_f32_16x16x32_bf16 v[112:115], v[154:157], v[170:173], v[112:115]
	v_mfma_f32_16x16x32_bf16 v[100:103], v[146:149], v[182:185], v[100:103]
	v_mfma_f32_16x16x32_bf16 v[96:99], v[154:157], v[182:185], v[96:99]
	v_mfma_f32_16x16x32_bf16 v[84:87], v[146:149], v[190:193], v[84:87]
	v_mfma_f32_16x16x32_bf16 v[80:83], v[154:157], v[190:193], v[80:83]
	s_setprio 0
	s_barrier
	s_add_i32 s14, 0, 0x1c000
	s_add_i32 s8, s46, s18
	v_add_u32_e32 v206, s14, v139
	s_mov_b32 m0, s8
	ds_read_b128 v[194:197], v206
	ds_read_b128 v[198:201], v206 offset:1024
	ds_read_b128 v[202:205], v206 offset:2048
	ds_read_b128 v[206:209], v206 offset:3072
	global_load_lds_dwordx4 v176, s[98:99]
	s_add_i32 m0, s8, 0x2000
	s_nop 0
	global_load_lds_dwordx4 v128, s[98:99]
	s_barrier
	s_waitcnt lgkmcnt(0)
	s_setprio 1
	v_mfma_f32_16x16x32_bf16 v[108:111], v[194:197], v[158:161], v[108:111]
	v_mfma_f32_16x16x32_bf16 v[104:107], v[202:205], v[158:161], v[104:107]
	v_mfma_f32_16x16x32_bf16 v[92:95], v[194:197], v[166:169], v[92:95]
	v_mfma_f32_16x16x32_bf16 v[88:91], v[202:205], v[166:169], v[88:91]
	v_mfma_f32_16x16x32_bf16 v[76:79], v[194:197], v[178:181], v[76:79]
	v_mfma_f32_16x16x32_bf16 v[72:75], v[202:205], v[178:181], v[72:75]
	v_mfma_f32_16x16x32_bf16 v[68:71], v[194:197], v[186:189], v[68:71]
	v_mfma_f32_16x16x32_bf16 v[64:67], v[202:205], v[186:189], v[64:67]
	v_mfma_f32_16x16x32_bf16 v[108:111], v[198:201], v[162:165], v[108:111]
	v_mfma_f32_16x16x32_bf16 v[104:107], v[206:209], v[162:165], v[104:107]
	v_mfma_f32_16x16x32_bf16 v[92:95], v[198:201], v[170:173], v[92:95]
	v_mfma_f32_16x16x32_bf16 v[88:91], v[206:209], v[170:173], v[88:91]
	v_mfma_f32_16x16x32_bf16 v[76:79], v[198:201], v[182:185], v[76:79]
	v_mfma_f32_16x16x32_bf16 v[72:75], v[206:209], v[182:185], v[72:75]
	v_mfma_f32_16x16x32_bf16 v[68:71], v[198:201], v[190:193], v[68:71]
	v_mfma_f32_16x16x32_bf16 v[64:67], v[206:209], v[190:193], v[64:67]
	s_setprio 0
	s_mov_b32 m0, s27
	s_barrier
	ds_read_b128 v[158:161], v141 offset:49152
	ds_read_b128 v[162:165], v141 offset:50176
	ds_read_b128 v[166:169], v141 offset:51200
	ds_read_b128 v[170:173], v141 offset:52224
	ds_read_b128 v[178:181], v141 offset:53248
	ds_read_b128 v[182:185], v141 offset:54272
	ds_read_b128 v[186:189], v141 offset:55296
	ds_read_b128 v[190:193], v141 offset:56320
	global_load_lds_dwordx4 v132, s[100:101]
	s_mov_b32 m0, s28
	s_nop 0
	global_load_lds_dwordx4 v130, s[100:101]
	s_barrier
; #define PG8_STAGE(bufoff, gbase, voff) do { _Pragma("unroll") for (int _i = 0; _i < 2; ++_i) \
;         __builtin_amdgcn_global_load_lds((const unsigned*)((const char*)(gbase) + (voff)[_i]), (PG8_LAS unsigned*)(lds + (bufoff) + ldsw + _i * 8192), 16, 0, 0); } while (0)
; #define PG8_MMA(ai, bj, At, Bt) do { __builtin_amdgcn_s_setprio(1); _Pragma("unroll") for (int m = 0; m < 4; ++m) _Pragma("unroll") for (int n = 0; n < 2; ++n) _Pragma("unroll") for (int k = 0; k < 2; ++k) \
;         acc[ai][bj][m][n] = __builtin_amdgcn_mfma_f32_16x16x32_bf16(Bt[n][k], At[m][k], acc[ai][bj][m][n], 0, 0, 0); __builtin_amdgcn_s_setprio(0); } while (0)
; #define PG8_WAIT_V(n) asm volatile("s_waitcnt vmcnt(" #n ")" ::: "memory")
; #define PG8_WAIT_L(n) asm volatile("s_waitcnt lgkmcnt(" #n ")" ::: "memory")
; #define PG8_BAR __builtin_amdgcn_s_barrier()
; #define PG8_SCHED __builtin_amdgcn_sched_barrier(0)
; template <class Epi, class Sched>
; __device__ __forceinline__ void gemm_phase(PG8_LAS unsigned char* lds, const Gemm g, const Sched& S, const Epi& E) {
;     ...
;             PG8_BAR; PG8_WAIT_L(0); PG8_MMA(1, 0, At, B0); PG8_BAR; PG8_SCHED;
;             PG8_STAGE(PG8_SB(1, 1), b3 + hstep, voffB);
;             PG8_WAIT_V(6); PG8_BAR; PG8_MMA(1, 1, At, B1); PG8_BAR;
	s_waitcnt lgkmcnt(0)
	s_setprio 1
	v_mfma_f32_16x16x32_bf16 v[60:63], v[142:145], v[158:161], v[60:63]
	v_mfma_f32_16x16x32_bf16 v[56:59], v[150:153], v[158:161], v[56:59]
	v_mfma_f32_16x16x32_bf16 v[52:55], v[142:145], v[166:169], v[52:55]
	v_mfma_f32_16x16x32_bf16 v[48:51], v[150:153], v[166:169], v[48:51]
	v_mfma_f32_16x16x32_bf16 v[36:39], v[142:145], v[178:181], v[36:39]
	v_mfma_f32_16x16x32_bf16 v[32:35], v[150:153], v[178:181], v[32:35]
	v_mfma_f32_16x16x32_bf16 v[20:23], v[142:145], v[186:189], v[20:23]
	v_mfma_f32_16x16x32_bf16 v[16:19], v[150:153], v[186:189], v[16:19]
	v_mfma_f32_16x16x32_bf16 v[60:63], v[146:149], v[162:165], v[60:63]
	v_mfma_f32_16x16x32_bf16 v[56:59], v[154:157], v[162:165], v[56:59]
	v_mfma_f32_16x16x32_bf16 v[52:55], v[146:149], v[170:173], v[52:55]
	v_mfma_f32_16x16x32_bf16 v[48:51], v[154:157], v[170:173], v[48:51]
	v_mfma_f32_16x16x32_bf16 v[36:39], v[146:149], v[182:185], v[36:39]
	v_mfma_f32_16x16x32_bf16 v[32:35], v[154:157], v[182:185], v[32:35]
	v_mfma_f32_16x16x32_bf16 v[20:23], v[146:149], v[190:193], v[20:23]
	v_mfma_f32_16x16x32_bf16 v[16:19], v[154:157], v[190:193], v[16:19]
	s_setprio 0
	s_barrier
	s_add_u32 s8, s12, 0xb0080
	s_addc_u32 s9, s13, 0
	s_add_i32 s12, s14, s18
	s_mov_b32 m0, s12
	s_nop 0
	global_load_lds_dwordx4 v176, s[8:9]
	s_add_i32 m0, s12, 0x2000
	s_nop 0
	global_load_lds_dwordx4 v128, s[8:9]
	s_waitcnt vmcnt(6)
	s_barrier
	s_setprio 1
	v_mfma_f32_16x16x32_bf16 v[44:47], v[194:197], v[158:161], v[44:47]
	v_mfma_f32_16x16x32_bf16 v[40:43], v[202:205], v[158:161], v[40:43]
	v_mfma_f32_16x16x32_bf16 v[28:31], v[194:197], v[166:169], v[28:31]
	v_mfma_f32_16x16x32_bf16 v[24:27], v[202:205], v[166:169], v[24:27]
	v_mfma_f32_16x16x32_bf16 v[12:15], v[194:197], v[178:181], v[12:15]
	v_mfma_f32_16x16x32_bf16 v[8:11], v[202:205], v[178:181], v[8:11]
	v_mfma_f32_16x16x32_bf16 v[4:7], v[194:197], v[186:189], v[4:7]
	v_mfma_f32_16x16x32_bf16 v[0:3], v[202:205], v[186:189], v[0:3]
	v_mfma_f32_16x16x32_bf16 v[44:47], v[198:201], v[162:165], v[44:47]
	v_mfma_f32_16x16x32_bf16 v[40:43], v[206:209], v[162:165], v[40:43]
	v_mfma_f32_16x16x32_bf16 v[28:31], v[198:201], v[170:173], v[28:31]
	v_mfma_f32_16x16x32_bf16 v[24:27], v[206:209], v[170:173], v[24:27]
	v_mfma_f32_16x16x32_bf16 v[12:15], v[198:201], v[182:185], v[12:15]
	v_mfma_f32_16x16x32_bf16 v[8:11], v[206:209], v[182:185], v[8:11]
	v_mfma_f32_16x16x32_bf16 v[4:7], v[198:201], v[190:193], v[4:7]
	v_mfma_f32_16x16x32_bf16 v[0:3], v[206:209], v[190:193], v[0:3]
	s_setprio 0
	s_add_i32 s45, s45, 2
	s_add_u32 s43, s43, 0x100
	s_addc_u32 s44, s44, 0
	s_cmp_gt_u32 s45, 41
	s_mov_b64 s[8:9], s[10:11]
	s_barrier
	s_cbranch_scc0 .LBB0_96
; __device__ __forceinline__ unsigned cvtpk(float lo, float hi) { const f32x2 v = (f32x2){lo, hi}; const bf16v2 b = __builtin_convertvector(v, bf16v2); return __builtin_bit_cast(unsigned, b); }
; #define PG8_WAIT_V(n) asm volatile("s_waitcnt vmcnt(" #n ")" ::: "memory")
; #define PG8_BAR __builtin_amdgcn_s_barrier()
; template <class Epi, class Sched>
; __device__ __forceinline__ void gemm_phase(PG8_LAS unsigned char* lds, const Gemm g, const Sched& S, const Epi& E) {
;     ...
;         if constexpr (!Epi::AFTER_DRAIN) { E(acc, cur, wr, wc, fr, fq); S.done(cur); }
;         if (!has_next) break;
; #pragma unroll
;         for (int a = 0; a < 2; ++a)
; #pragma unroll
;             for (int b = 0; b < 2; ++b)
; #pragma unroll
;                 for (int m = 0; m < 4; ++m)
; #pragma unroll
;                     for (int n = 0; n < 2; ++n) acc[a][b][m][n] = (f32x4){0.f, 0.f, 0.f, 0.f};
;         cur = nxt; cA = nA; cB = nB; ++ui;
;     }
;     PG8_WAIT_V(0);
;     if (wr == 0) PG8_BAR;
;     __device__ __forceinline__ void operator()(const f32x4 (&acc)[2][2][4][2], const pg8::Unit& u, int wr, int wc, int fr, int fq) const {
;         const int row0 = u.pm * 256 + wr * 64 + fr, col0 = u.pn * 256 + wc * 32 + 8 * fq;
; #pragma unroll
;         for (int ai = 0; ai < 2; ++ai)
; #pragma unroll
;             for (int m = 0; m < 4; ++m) { bf16_t* rowp = O + (size_t)(row0 + ai * 128 + m * 16) * ldc + col0;
; #pragma unroll
;                 for (int bj = 0; bj < 2; ++bj) { const f32x4 v0 = acc[ai][bj][m][0], v1 = acc[ai][bj][m][1];
;                     u32x4 w; w.x = cvtpk(v0[0], v0[1]); w.y = cvtpk(v0[2], v0[3]); w.z = cvtpk(v1[0], v1[1]); w.w = cvtpk(v1[2], v1[3]);
;                     *(u32x4*)(rowp + bj * 128) = w; } }
;     }
	v_lshl_add_u32 v142, s29, 8, v138
	v_lshl_or_b32 v144, s34, 8, v140
	v_ashrrev_i32_e32 v143, 31, v142
	v_readlane_b32 s8, v253, 18
	v_cvt_pk_bf16_f32 v108, v108, v109
	v_cvt_pk_bf16_f32 v109, v110, v111
	v_cvt_pk_bf16_f32 v110, v104, v105
	v_or_b32_e32 v104, 16, v142
	v_cvt_pk_bf16_f32 v92, v92, v93
	v_cvt_pk_bf16_f32 v93, v94, v95
	v_cvt_pk_bf16_f32 v94, v88, v89
	v_or_b32_e32 v88, 32, v142
	v_cvt_pk_bf16_f32 v76, v76, v77
	v_cvt_pk_bf16_f32 v77, v78, v79
	v_cvt_pk_bf16_f32 v78, v72, v73
	v_or_b32_e32 v72, 48, v142
	v_ashrrev_i32_e32 v145, 31, v144
	v_lshlrev_b64 v[146:147], 11, v[142:143]
	v_readlane_b32 s9, v253, 19
	v_ashrrev_i32_e32 v105, 31, v104
	v_ashrrev_i32_e32 v89, 31, v88
	v_ashrrev_i32_e32 v73, 31, v72
	v_lshl_add_u64 v[146:147], s[8:9], 0, v[146:147]
	v_lshlrev_b64 v[144:145], 1, v[144:145]
	v_lshlrev_b64 v[104:105], 11, v[104:105]
	v_lshlrev_b64 v[88:89], 11, v[88:89]
	v_lshlrev_b64 v[72:73], 11, v[72:73]
	v_lshl_add_u64 v[146:147], v[146:147], 0, v[144:145]
	v_lshl_add_u64 v[104:105], s[8:9], 0, v[104:105]
	v_lshl_add_u64 v[88:89], s[8:9], 0, v[88:89]
	v_lshl_add_u64 v[72:73], s[8:9], 0, v[72:73]
	s_mov_b64 s[8:9], 0x40000
	v_cvt_pk_bf16_f32 v68, v68, v69
	v_cvt_pk_bf16_f32 v69, v70, v71
	v_cvt_pk_bf16_f32 v70, v64, v65
	v_lshl_add_u64 v[64:65], v[146:147], 0, s[8:9]
	v_cvt_pk_bf16_f32 v60, v60, v61
	v_cvt_pk_bf16_f32 v61, v62, v63
	v_cvt_pk_bf16_f32 v62, v56, v57
	v_add_co_u32_e32 v56, vcc, s2, v146
	v_cvt_pk_bf16_f32 v44, v44, v45
	v_cvt_pk_bf16_f32 v45, v46, v47
	v_cvt_pk_bf16_f32 v46, v40, v41
	v_cvt_pk_bf16_f32 v47, v42, v43
	s_mov_b64 s[8:9], 0x48000
	v_addc_co_u32_e32 v57, vcc, 0, v147, vcc
	global_store_dwordx4 v[64:65], v[44:47], off offset:256
	v_cvt_pk_bf16_f32 v28, v28, v29
	v_cvt_pk_bf16_f32 v29, v30, v31
	v_lshl_add_u64 v[44:45], v[146:147], 0, s[8:9]
	s_mov_b32 s8, 0x48000
	v_add_co_u32_e32 v46, vcc, s8, v146
	v_cvt_pk_bf16_f32 v30, v24, v25
	v_cvt_pk_bf16_f32 v31, v26, v27
	s_mov_b64 s[8:9], 0x50000
	v_addc_co_u32_e32 v47, vcc, 0, v147, vcc
	global_store_dwordx4 v[44:45], v[28:31], off offset:256
	v_cvt_pk_bf16_f32 v12, v12, v13
	v_cvt_pk_bf16_f32 v13, v14, v15
	v_lshl_add_u64 v[28:29], v[146:147], 0, s[8:9]
	s_mov_b32 s8, 0x50000
	v_add_co_u32_e32 v30, vcc, s8, v146
	v_cvt_pk_bf16_f32 v14, v8, v9
	v_cvt_pk_bf16_f32 v15, v10, v11
	s_mov_b64 s[8:9], 0x58000
	v_cvt_pk_bf16_f32 v111, v106, v107
	v_addc_co_u32_e32 v31, vcc, 0, v147, vcc
	global_store_dwordx4 v[28:29], v[12:15], off offset:256
	global_store_dwordx4 v[146:147], v[108:111], off offset:256
	v_cvt_pk_bf16_f32 v95, v90, v91
	v_lshl_add_u64 v[12:13], v[146:147], 0, s[8:9]
	s_mov_b32 s8, 0x58000
	v_lshl_add_u64 v[108:109], v[104:105], 0, v[144:145]
	v_add_co_u32_e32 v14, vcc, s8, v146
	global_store_dwordx4 v[108:109], v[92:95], off offset:256
	v_cvt_pk_bf16_f32 v79, v74, v75
	v_addc_co_u32_e32 v15, vcc, 0, v147, vcc
	v_lshl_add_u64 v[92:93], v[88:89], 0, v[144:145]
	v_cvt_pk_bf16_f32 v124, v124, v125
	v_cvt_pk_bf16_f32 v125, v126, v127
	v_cvt_pk_bf16_f32 v126, v120, v121
	v_cvt_pk_bf16_f32 v127, v122, v123
	v_cvt_pk_bf16_f32 v104, v116, v117
	v_cvt_pk_bf16_f32 v105, v118, v119
	v_cvt_pk_bf16_f32 v106, v112, v113
	v_cvt_pk_bf16_f32 v107, v114, v115
	v_cvt_pk_bf16_f32 v88, v100, v101
	v_cvt_pk_bf16_f32 v89, v102, v103
	v_cvt_pk_bf16_f32 v90, v96, v97
	v_cvt_pk_bf16_f32 v91, v98, v99
	global_store_dwordx4 v[92:93], v[76:79], off offset:256
	v_cvt_pk_bf16_f32 v74, v80, v81
	v_cvt_pk_bf16_f32 v75, v82, v83
	v_lshl_add_u64 v[76:77], v[72:73], 0, v[144:145]
	v_cvt_pk_bf16_f32 v72, v84, v85
	v_cvt_pk_bf16_f32 v73, v86, v87
	v_cvt_pk_bf16_f32 v71, v66, v67
	v_cvt_pk_bf16_f32 v63, v58, v59
	v_cvt_pk_bf16_f32 v40, v52, v53
	v_cvt_pk_bf16_f32 v41, v54, v55
	v_cvt_pk_bf16_f32 v42, v48, v49
	v_cvt_pk_bf16_f32 v43, v50, v51
	v_cvt_pk_bf16_f32 v24, v36, v37
	v_cvt_pk_bf16_f32 v25, v38, v39
	v_cvt_pk_bf16_f32 v26, v32, v33
	v_cvt_pk_bf16_f32 v27, v34, v35
	v_cvt_pk_bf16_f32 v8, v20, v21
	v_cvt_pk_bf16_f32 v9, v22, v23
	v_cvt_pk_bf16_f32 v10, v16, v17
	v_cvt_pk_bf16_f32 v11, v18, v19
	v_cvt_pk_bf16_f32 v4, v4, v5
	v_cvt_pk_bf16_f32 v5, v6, v7
	v_cvt_pk_bf16_f32 v6, v0, v1
	v_cvt_pk_bf16_f32 v7, v2, v3
	s_and_b64 vcc, exec, s[38:39]
	s_mov_b32 s34, s40
	s_mov_b32 s29, s41
	s_mov_b64 s[10:11], s[4:5]
	s_mov_b64 s[8:9], s[0:1]
	global_store_dwordx4 v[146:147], v[124:127], off
	global_store_dwordx4 v[108:109], v[104:107], off
	global_store_dwordx4 v[92:93], v[88:91], off
	global_store_dwordx4 v[76:77], v[72:75], off
	global_store_dwordx4 v[76:77], v[68:71], off offset:256
	global_store_dwordx4 v[56:57], v[60:63], off
	global_store_dwordx4 v[46:47], v[40:43], off
	global_store_dwordx4 v[30:31], v[24:27], off
	global_store_dwordx4 v[14:15], v[8:11], off
	global_store_dwordx4 v[12:13], v[4:7], off offset:256
	s_cbranch_vccz .LBB0_89
	s_waitcnt vmcnt(0)
	s_cmpk_gt_u32 s17, 0xff
	v_readlane_b32 s2, v254, 59
	s_cbranch_scc1 .LBB0_100
	s_barrier

; #define PG8_STAGE(bufoff, gbase, voff) do { _Pragma("unroll") for (int _i = 0; _i < 2; ++_i) \
;         __builtin_amdgcn_global_load_lds((const unsigned*)((const char*)(gbase) + (voff)[_i]), (PG8_LAS unsigned*)(lds + (bufoff) + ldsw + _i * 8192), 16, 0, 0); } while (0)
; #define PG8_LDA(dst, b, h) do { _Pragma("unroll") for (int m = 0; m < 4; ++m) _Pragma("unroll") for (int k = 0; k < 2; ++k) dst[m][k] = *(const PG8_LAS bf16x8*)(lds + PG8_SA(b, h) + aoff + m * 2048 + k * 1024); } while (0)
; #define PG8_LDB(dst, b, h) do { _Pragma("unroll") for (int n = 0; n < 2; ++n) _Pragma("unroll") for (int k = 0; k < 2; ++k) dst[n][k] = *(const PG8_LAS bf16x8*)(lds + PG8_SB(b, h) + boff + n * 2048 + k * 1024); } while (0)
; #define PG8_MMA(ai, bj, At, Bt) do { __builtin_amdgcn_s_setprio(1); _Pragma("unroll") for (int m = 0; m < 4; ++m) _Pragma("unroll") for (int n = 0; n < 2; ++n) _Pragma("unroll") for (int k = 0; k < 2; ++k) \
;         acc[ai][bj][m][n] = __builtin_amdgcn_mfma_f32_16x16x32_bf16(Bt[n][k], At[m][k], acc[ai][bj][m][n], 0, 0, 0); __builtin_amdgcn_s_setprio(0); } while (0)
; #define PG8_WAIT_V(n) asm volatile("s_waitcnt vmcnt(" #n ")" ::: "memory")
; template <class Epi, class Sched>
; __device__ __forceinline__ void gemm_phase(PG8_LAS unsigned char* lds, const Gemm g, const Sched& S, const Epi& E) {
;     ...
;         for (int t = 0; t < nt; t += 2) {
;             const bool last = (t == nt - 2);
;             const char* a1 = cA + (size_t)(t + 1) * kstep;
;             const char* a2 = last ? nA : cA + (size_t)(t + 2) * kstep; const char* b2 = last ? nB : cB + (size_t)(t + 2) * kstep;
;             const char* a3 = a2 + kstep; const char* b3 = b2 + kstep;
;             if (last && has_next) S.a_ready(nxt);
;             PG8_LDB(B0, 0, 0); PG8_SCHED; PG8_LDA(At, 0, 0); PG8_STAGE(PG8_SA(1, 1), a1 + hstep, voffA);
;             PG8_WAIT_L(8); PG8_BAR; PG8_WAIT_L(0); PG8_MMA(0, 0, At, B0); PG8_BAR; PG8_SCHED;
;             PG8_LDB(B1, 0, 1); PG8_STAGE(PG8_SB(0, 0), b2, voffB);
;             PG8_BAR; PG8_WAIT_L(0); PG8_MMA(0, 1, At, B1); PG8_BAR;
;             PG8_LDA(At, 0, 1); PG8_STAGE(PG8_SA(0, 0), a2, voffA);
;             PG8_BAR; PG8_WAIT_L(0); PG8_MMA(1, 0, At, B0); PG8_BAR; PG8_SCHED;
;             PG8_STAGE(PG8_SB(0, 1), b2 + hstep, voffB);
;             PG8_WAIT_V(6); PG8_BAR; PG8_MMA(1, 1, At, B1); PG8_BAR;
.LBB0_114:
	s_add_u32 s14, s12, 0xfffc0080
	s_addc_u32 s15, s13, -1
	s_add_i32 s46, 0, 0x10000
	v_add_u32_e32 v154, s46, v143
	ds_read_b128 v[138:141], v154
	ds_read_b128 v[146:149], v154 offset:1024
	ds_read_b128 v[150:153], v154 offset:2048
	ds_read_b128 v[154:157], v154 offset:3072
	s_cmp_eq_u32 s45, 12
	s_cselect_b32 s17, s5, s15
	s_cselect_b32 s16, s40, s14
	s_cselect_b32 s15, s1, s44
	s_cselect_b32 s14, s41, s43
	s_add_i32 m0, s11, 0xc000
	ds_read_b128 v[158:161], v145
	ds_read_b128 v[162:165], v145 offset:1024
	ds_read_b128 v[166:169], v145 offset:2048
	ds_read_b128 v[170:173], v145 offset:3072
	ds_read_b128 v[178:181], v145 offset:4096
	ds_read_b128 v[182:185], v145 offset:5120
	ds_read_b128 v[186:189], v145 offset:6144
	ds_read_b128 v[190:193], v145 offset:7168
	global_load_lds_dwordx4 v134, s[12:13]
	s_add_i32 m0, s11, 0xe000
	s_nop 0
	global_load_lds_dwordx4 v136, s[12:13]
	s_waitcnt lgkmcnt(8)
	s_barrier
	s_waitcnt lgkmcnt(0)
	s_setprio 1
	v_mfma_f32_16x16x32_bf16 v[124:127], v[138:141], v[158:161], v[124:127]
	v_mfma_f32_16x16x32_bf16 v[116:119], v[150:153], v[158:161], v[116:119]
	v_mfma_f32_16x16x32_bf16 v[108:111], v[138:141], v[166:169], v[108:111]
	v_mfma_f32_16x16x32_bf16 v[100:103], v[150:153], v[166:169], v[100:103]
	v_mfma_f32_16x16x32_bf16 v[92:95], v[138:141], v[178:181], v[92:95]
	v_mfma_f32_16x16x32_bf16 v[84:87], v[150:153], v[178:181], v[84:87]
	v_mfma_f32_16x16x32_bf16 v[76:79], v[138:141], v[186:189], v[76:79]
	v_mfma_f32_16x16x32_bf16 v[68:71], v[150:153], v[186:189], v[68:71]
	v_mfma_f32_16x16x32_bf16 v[124:127], v[146:149], v[162:165], v[124:127]
	v_mfma_f32_16x16x32_bf16 v[116:119], v[154:157], v[162:165], v[116:119]
	v_mfma_f32_16x16x32_bf16 v[108:111], v[146:149], v[170:173], v[108:111]
	v_mfma_f32_16x16x32_bf16 v[100:103], v[154:157], v[170:173], v[100:103]
	v_mfma_f32_16x16x32_bf16 v[92:95], v[146:149], v[182:185], v[92:95]
	v_mfma_f32_16x16x32_bf16 v[84:87], v[154:157], v[182:185], v[84:87]
	v_mfma_f32_16x16x32_bf16 v[76:79], v[146:149], v[190:193], v[76:79]
	v_mfma_f32_16x16x32_bf16 v[68:71], v[154:157], v[190:193], v[68:71]
	s_setprio 0
	s_barrier
	s_add_i32 s48, 0, 0x14000
	v_add_u32_e32 v174, s48, v143
	s_add_i32 s46, s46, s20
	ds_read_b128 v[194:197], v174
	ds_read_b128 v[198:201], v174 offset:1024
	ds_read_b128 v[202:205], v174 offset:2048
	ds_read_b128 v[206:209], v174 offset:3072
	s_add_u32 s98, s14, 0x80
	s_addc_u32 s99, s15, 0
	s_mov_b32 m0, s46
	s_nop 0
	global_load_lds_dwordx4 v176, s[14:15]
	s_add_i32 m0, s46, 0x2000
	s_nop 0
	global_load_lds_dwordx4 v128, s[14:15]
	s_barrier
	s_waitcnt lgkmcnt(0)
	s_setprio 1
	v_mfma_f32_16x16x32_bf16 v[120:123], v[194:197], v[158:161], v[120:123]
	v_mfma_f32_16x16x32_bf16 v[112:115], v[202:205], v[158:161], v[112:115]
	v_mfma_f32_16x16x32_bf16 v[104:107], v[194:197], v[166:169], v[104:107]
	v_mfma_f32_16x16x32_bf16 v[96:99], v[202:205], v[166:169], v[96:99]
	v_mfma_f32_16x16x32_bf16 v[88:91], v[194:197], v[178:181], v[88:91]
	v_mfma_f32_16x16x32_bf16 v[80:83], v[202:205], v[178:181], v[80:83]
	v_mfma_f32_16x16x32_bf16 v[72:75], v[194:197], v[186:189], v[72:75]
	v_mfma_f32_16x16x32_bf16 v[64:67], v[202:205], v[186:189], v[64:67]
	v_mfma_f32_16x16x32_bf16 v[120:123], v[198:201], v[162:165], v[120:123]
	v_mfma_f32_16x16x32_bf16 v[112:115], v[206:209], v[162:165], v[112:115]
	v_mfma_f32_16x16x32_bf16 v[104:107], v[198:201], v[170:173], v[104:107]
	v_mfma_f32_16x16x32_bf16 v[96:99], v[206:209], v[170:173], v[96:99]
	v_mfma_f32_16x16x32_bf16 v[88:91], v[198:201], v[182:185], v[88:91]
	v_mfma_f32_16x16x32_bf16 v[80:83], v[206:209], v[182:185], v[80:83]
	v_mfma_f32_16x16x32_bf16 v[72:75], v[198:201], v[190:193], v[72:75]
	v_mfma_f32_16x16x32_bf16 v[64:67], v[206:209], v[190:193], v[64:67]
	s_setprio 0
	s_mov_b32 m0, s11
	s_add_u32 s100, s16, 0x80
	s_addc_u32 s101, s17, 0
	s_barrier
	ds_read_b128 v[158:161], v145 offset:16384
	ds_read_b128 v[162:165], v145 offset:17408
	ds_read_b128 v[166:169], v145 offset:18432
	ds_read_b128 v[170:173], v145 offset:19456
	ds_read_b128 v[178:181], v145 offset:20480
	ds_read_b128 v[182:185], v145 offset:21504
	ds_read_b128 v[186:189], v145 offset:22528
	ds_read_b128 v[190:193], v145 offset:23552
	global_load_lds_dwordx4 v132, s[16:17]
	s_mov_b32 m0, s22
	s_nop 0
	global_load_lds_dwordx4 v130, s[16:17]
	s_barrier
	s_waitcnt lgkmcnt(0)
	s_setprio 1
	v_mfma_f32_16x16x32_bf16 v[60:63], v[138:141], v[158:161], v[60:63]
	v_mfma_f32_16x16x32_bf16 v[52:55], v[150:153], v[158:161], v[52:55]
	v_mfma_f32_16x16x32_bf16 v[44:47], v[138:141], v[166:169], v[44:47]
	v_mfma_f32_16x16x32_bf16 v[36:39], v[150:153], v[166:169], v[36:39]
	v_mfma_f32_16x16x32_bf16 v[28:31], v[138:141], v[178:181], v[28:31]
	v_mfma_f32_16x16x32_bf16 v[20:23], v[150:153], v[178:181], v[20:23]
	v_mfma_f32_16x16x32_bf16 v[12:15], v[138:141], v[186:189], v[12:15]
	v_mfma_f32_16x16x32_bf16 v[4:7], v[150:153], v[186:189], v[4:7]
	v_mfma_f32_16x16x32_bf16 v[60:63], v[146:149], v[162:165], v[60:63]
	v_mfma_f32_16x16x32_bf16 v[52:55], v[154:157], v[162:165], v[52:55]
	v_mfma_f32_16x16x32_bf16 v[44:47], v[146:149], v[170:173], v[44:47]
	v_mfma_f32_16x16x32_bf16 v[36:39], v[154:157], v[170:173], v[36:39]
	v_mfma_f32_16x16x32_bf16 v[28:31], v[146:149], v[182:185], v[28:31]
	v_mfma_f32_16x16x32_bf16 v[20:23], v[154:157], v[182:185], v[20:23]
	v_mfma_f32_16x16x32_bf16 v[12:15], v[146:149], v[190:193], v[12:15]
	v_mfma_f32_16x16x32_bf16 v[4:7], v[154:157], v[190:193], v[4:7]
	s_setprio 0
	s_barrier
	s_add_u32 s46, s14, 0x40000
	s_addc_u32 s47, s15, 0
	s_add_i32 s48, s48, s20
	s_mov_b32 m0, s48
	s_nop 0
	global_load_lds_dwordx4 v176, s[46:47]
	s_add_i32 m0, s48, 0x2000
	s_nop 0
	global_load_lds_dwordx4 v128, s[46:47]
	s_waitcnt vmcnt(6)
	s_barrier
; #define PG8_STAGE(bufoff, gbase, voff) do { _Pragma("unroll") for (int _i = 0; _i < 2; ++_i) \
;         __builtin_amdgcn_global_load_lds((const unsigned*)((const char*)(gbase) + (voff)[_i]), (PG8_LAS unsigned*)(lds + (bufoff) + ldsw + _i * 8192), 16, 0, 0); } while (0)
; #define PG8_LDA(dst, b, h) do { _Pragma("unroll") for (int m = 0; m < 4; ++m) _Pragma("unroll") for (int k = 0; k < 2; ++k) dst[m][k] = *(const PG8_LAS bf16x8*)(lds + PG8_SA(b, h) + aoff + m * 2048 + k * 1024); } while (0)
; #define PG8_LDB(dst, b, h) do { _Pragma("unroll") for (int n = 0; n < 2; ++n) _Pragma("unroll") for (int k = 0; k < 2; ++k) dst[n][k] = *(const PG8_LAS bf16x8*)(lds + PG8_SB(b, h) + boff + n * 2048 + k * 1024); } while (0)
; #define PG8_MMA(ai, bj, At, Bt) do { __builtin_amdgcn_s_setprio(1); _Pragma("unroll") for (int m = 0; m < 4; ++m) _Pragma("unroll") for (int n = 0; n < 2; ++n) _Pragma("unroll") for (int k = 0; k < 2; ++k) \
;         acc[ai][bj][m][n] = __builtin_amdgcn_mfma_f32_16x16x32_bf16(Bt[n][k], At[m][k], acc[ai][bj][m][n], 0, 0, 0); __builtin_amdgcn_s_setprio(0); } while (0)
; #define PG8_WAIT_V(n) asm volatile("s_waitcnt vmcnt(" #n ")" ::: "memory")
; #define PG8_WAIT_L(n) asm volatile("s_waitcnt lgkmcnt(" #n ")" ::: "memory")
; #define PG8_BAR __builtin_amdgcn_s_barrier()
; #define PG8_SCHED __builtin_amdgcn_sched_barrier(0)
; template <class Epi, class Sched>
; __device__ __forceinline__ void gemm_phase(PG8_LAS unsigned char* lds, const Gemm g, const Sched& S, const Epi& E) {
;     ...
;             PG8_WAIT_V(6); PG8_BAR; PG8_MMA(1, 1, At, B1); PG8_BAR;
;             PG8_LDB(B0, 1, 0); PG8_SCHED; PG8_LDA(At, 1, 0); PG8_STAGE(PG8_SA(0, 1), a2 + hstep, voffA);
;             PG8_WAIT_L(8); PG8_BAR; PG8_WAIT_L(0); PG8_MMA(0, 0, At, B0); PG8_BAR; PG8_SCHED;
;             PG8_LDB(B1, 1, 1); PG8_STAGE(PG8_SB(1, 0), b3, voffB);
;             PG8_BAR; PG8_WAIT_L(0); PG8_MMA(0, 1, At, B1); PG8_BAR;
;             PG8_LDA(At, 1, 1); PG8_STAGE(PG8_SA(1, 0), a3, voffA);
	s_setprio 1
	v_mfma_f32_16x16x32_bf16 v[56:59], v[194:197], v[158:161], v[56:59]
	v_mfma_f32_16x16x32_bf16 v[48:51], v[202:205], v[158:161], v[48:51]
	v_mfma_f32_16x16x32_bf16 v[40:43], v[194:197], v[166:169], v[40:43]
	v_mfma_f32_16x16x32_bf16 v[32:35], v[202:205], v[166:169], v[32:35]
	v_mfma_f32_16x16x32_bf16 v[24:27], v[194:197], v[178:181], v[24:27]
	v_mfma_f32_16x16x32_bf16 v[16:19], v[202:205], v[178:181], v[16:19]
	v_mfma_f32_16x16x32_bf16 v[8:11], v[194:197], v[186:189], v[8:11]
	v_mfma_f32_16x16x32_bf16 v[0:3], v[202:205], v[186:189], v[0:3]
	v_mfma_f32_16x16x32_bf16 v[56:59], v[198:201], v[162:165], v[56:59]
	v_mfma_f32_16x16x32_bf16 v[48:51], v[206:209], v[162:165], v[48:51]
	v_mfma_f32_16x16x32_bf16 v[40:43], v[198:201], v[170:173], v[40:43]
	v_mfma_f32_16x16x32_bf16 v[32:35], v[206:209], v[170:173], v[32:35]
	v_mfma_f32_16x16x32_bf16 v[24:27], v[198:201], v[182:185], v[24:27]
	v_mfma_f32_16x16x32_bf16 v[16:19], v[206:209], v[182:185], v[16:19]
	v_mfma_f32_16x16x32_bf16 v[8:11], v[198:201], v[190:193], v[8:11]
	v_mfma_f32_16x16x32_bf16 v[0:3], v[206:209], v[190:193], v[0:3]
	s_setprio 0
	s_add_i32 s46, 0, 0x18000
	v_add_u32_e32 v154, s46, v143
	s_barrier
	ds_read_b128 v[138:141], v154
	ds_read_b128 v[146:149], v154 offset:1024
	ds_read_b128 v[150:153], v154 offset:2048
	ds_read_b128 v[154:157], v154 offset:3072
	s_add_u32 s16, s16, 0x40000
	s_addc_u32 s17, s17, 0
	s_mov_b32 m0, s23
	ds_read_b128 v[158:161], v145 offset:32768
	ds_read_b128 v[162:165], v145 offset:33792
	ds_read_b128 v[166:169], v145 offset:34816
	ds_read_b128 v[170:173], v145 offset:35840
	ds_read_b128 v[178:181], v145 offset:36864
	ds_read_b128 v[182:185], v145 offset:37888
	ds_read_b128 v[186:189], v145 offset:38912
	ds_read_b128 v[190:193], v145 offset:39936
	global_load_lds_dwordx4 v132, s[16:17]
	s_mov_b32 m0, s26
	s_nop 0
	global_load_lds_dwordx4 v130, s[16:17]
	s_waitcnt lgkmcnt(8)
	s_barrier
	s_waitcnt lgkmcnt(0)
	s_setprio 1
	v_mfma_f32_16x16x32_bf16 v[124:127], v[138:141], v[158:161], v[124:127]
	v_mfma_f32_16x16x32_bf16 v[116:119], v[150:153], v[158:161], v[116:119]
	v_mfma_f32_16x16x32_bf16 v[108:111], v[138:141], v[166:169], v[108:111]
	v_mfma_f32_16x16x32_bf16 v[100:103], v[150:153], v[166:169], v[100:103]
	v_mfma_f32_16x16x32_bf16 v[92:95], v[138:141], v[178:181], v[92:95]
	v_mfma_f32_16x16x32_bf16 v[84:87], v[150:153], v[178:181], v[84:87]
	v_mfma_f32_16x16x32_bf16 v[76:79], v[138:141], v[186:189], v[76:79]
	v_mfma_f32_16x16x32_bf16 v[68:71], v[150:153], v[186:189], v[68:71]
	v_mfma_f32_16x16x32_bf16 v[124:127], v[146:149], v[162:165], v[124:127]
	v_mfma_f32_16x16x32_bf16 v[116:119], v[154:157], v[162:165], v[116:119]
	v_mfma_f32_16x16x32_bf16 v[108:111], v[146:149], v[170:173], v[108:111]
	v_mfma_f32_16x16x32_bf16 v[100:103], v[154:157], v[170:173], v[100:103]
	v_mfma_f32_16x16x32_bf16 v[92:95], v[146:149], v[182:185], v[92:95]
	v_mfma_f32_16x16x32_bf16 v[84:87], v[154:157], v[182:185], v[84:87]
	v_mfma_f32_16x16x32_bf16 v[76:79], v[146:149], v[190:193], v[76:79]
	v_mfma_f32_16x16x32_bf16 v[68:71], v[154:157], v[190:193], v[68:71]
	s_setprio 0
	s_barrier
	s_add_i32 s16, 0, 0x1c000
	s_add_i32 s17, s46, s20
	v_add_u32_e32 v206, s16, v143
	s_mov_b32 m0, s17
	ds_read_b128 v[194:197], v206
	ds_read_b128 v[198:201], v206 offset:1024
	ds_read_b128 v[202:205], v206 offset:2048
	ds_read_b128 v[206:209], v206 offset:3072
	global_load_lds_dwordx4 v176, s[98:99]
	s_add_i32 m0, s17, 0x2000
	s_nop 0
	global_load_lds_dwordx4 v128, s[98:99]
	s_barrier
	s_waitcnt lgkmcnt(0)
	s_setprio 1
	v_mfma_f32_16x16x32_bf16 v[120:123], v[194:197], v[158:161], v[120:123]
	v_mfma_f32_16x16x32_bf16 v[112:115], v[202:205], v[158:161], v[112:115]
	v_mfma_f32_16x16x32_bf16 v[104:107], v[194:197], v[166:169], v[104:107]
	v_mfma_f32_16x16x32_bf16 v[96:99], v[202:205], v[166:169], v[96:99]
	v_mfma_f32_16x16x32_bf16 v[88:91], v[194:197], v[178:181], v[88:91]
	v_mfma_f32_16x16x32_bf16 v[80:83], v[202:205], v[178:181], v[80:83]
	v_mfma_f32_16x16x32_bf16 v[72:75], v[194:197], v[186:189], v[72:75]
	v_mfma_f32_16x16x32_bf16 v[64:67], v[202:205], v[186:189], v[64:67]
	v_mfma_f32_16x16x32_bf16 v[120:123], v[198:201], v[162:165], v[120:123]
	v_mfma_f32_16x16x32_bf16 v[112:115], v[206:209], v[162:165], v[112:115]
	v_mfma_f32_16x16x32_bf16 v[104:107], v[198:201], v[170:173], v[104:107]
	v_mfma_f32_16x16x32_bf16 v[96:99], v[206:209], v[170:173], v[96:99]
	v_mfma_f32_16x16x32_bf16 v[88:91], v[198:201], v[182:185], v[88:91]
	v_mfma_f32_16x16x32_bf16 v[80:83], v[206:209], v[182:185], v[80:83]
	v_mfma_f32_16x16x32_bf16 v[72:75], v[198:201], v[190:193], v[72:75]
	v_mfma_f32_16x16x32_bf16 v[64:67], v[206:209], v[190:193], v[64:67]
	s_setprio 0
	s_mov_b32 m0, s28
	s_barrier
	ds_read_b128 v[158:161], v145 offset:49152
	ds_read_b128 v[162:165], v145 offset:50176
	ds_read_b128 v[166:169], v145 offset:51200
	ds_read_b128 v[170:173], v145 offset:52224
	ds_read_b128 v[178:181], v145 offset:53248
	ds_read_b128 v[182:185], v145 offset:54272
	ds_read_b128 v[186:189], v145 offset:55296
	ds_read_b128 v[190:193], v145 offset:56320
	global_load_lds_dwordx4 v132, s[100:101]
	s_mov_b32 m0, s29
	s_nop 0
	global_load_lds_dwordx4 v130, s[100:101]
	s_barrier
; __device__ __forceinline__ unsigned cvtpk(float lo, float hi) { const f32x2 v = (f32x2){lo, hi}; const bf16v2 b = __builtin_convertvector(v, bf16v2); return __builtin_bit_cast(unsigned, b); }
; __device__ __forceinline__ float siluf_(float x) { return x * sigmoidf_(x); }
; #define PG8_STAGE(bufoff, gbase, voff) do { _Pragma("unroll") for (int _i = 0; _i < 2; ++_i) \
;         __builtin_amdgcn_global_load_lds((const unsigned*)((const char*)(gbase) + (voff)[_i]), (PG8_LAS unsigned*)(lds + (bufoff) + ldsw + _i * 8192), 16, 0, 0); } while (0)
; #define PG8_MMA(ai, bj, At, Bt) do { __builtin_amdgcn_s_setprio(1); _Pragma("unroll") for (int m = 0; m < 4; ++m) _Pragma("unroll") for (int n = 0; n < 2; ++n) _Pragma("unroll") for (int k = 0; k < 2; ++k) \
;         acc[ai][bj][m][n] = __builtin_amdgcn_mfma_f32_16x16x32_bf16(Bt[n][k], At[m][k], acc[ai][bj][m][n], 0, 0, 0); __builtin_amdgcn_s_setprio(0); } while (0)
; #define PG8_WAIT_V(n) asm volatile("s_waitcnt vmcnt(" #n ")" ::: "memory")
; #define PG8_WAIT_L(n) asm volatile("s_waitcnt lgkmcnt(" #n ")" ::: "memory")
; #define PG8_BAR __builtin_amdgcn_s_barrier()
; template <class Epi, class Sched>
; __device__ __forceinline__ void gemm_phase(PG8_LAS unsigned char* lds, const Gemm g, const Sched& S, const Epi& E) {
;     ...
;             PG8_BAR; PG8_WAIT_L(0); PG8_MMA(1, 0, At, B0); PG8_BAR; PG8_SCHED;
;             PG8_STAGE(PG8_SB(1, 1), b3 + hstep, voffB);
;             PG8_WAIT_V(6); PG8_BAR; PG8_MMA(1, 1, At, B1); PG8_BAR;
;     __device__ __forceinline__ void operator()(const f32x4 (&acc)[2][2][4][2], const pg8::Unit& u, int wr, int wc, int fr, int fq) const {
;         const int row0 = u.pm * 256 + wr * 64 + fr, col0 = u.pn * 128 + wc * 32 + 8 * fq;
; #pragma unroll
;         for (int ai = 0; ai < 2; ++ai)
; #pragma unroll
;             for (int m = 0; m < 4; ++m) { bf16_t* rowp = O + (size_t)(row0 + ai * 128 + m * 16) * ldc + col0;
;                 const f32x4 g0 = acc[ai][0][m][0], g1 = acc[ai][0][m][1], u0 = acc[ai][1][m][0], u1 = acc[ai][1][m][1];
;                 u32x4 w; w.x = cvtpk(siluf_(g0[0]) * u0[0], siluf_(g0[1]) * u0[1]); w.y = cvtpk(siluf_(g0[2]) * u0[2], siluf_(g0[3]) * u0[3]);
;                 w.z = cvtpk(siluf_(g1[0]) * u1[0], siluf_(g1[1]) * u1[1]); w.w = cvtpk(siluf_(g1[2]) * u1[2], siluf_(g1[3]) * u1[3]);
;                 *(u32x4*)rowp = w; }
;     }
	s_waitcnt lgkmcnt(0)
	s_setprio 1
	v_mfma_f32_16x16x32_bf16 v[60:63], v[138:141], v[158:161], v[60:63]
	v_mfma_f32_16x16x32_bf16 v[52:55], v[150:153], v[158:161], v[52:55]
	v_mfma_f32_16x16x32_bf16 v[44:47], v[138:141], v[166:169], v[44:47]
	v_mfma_f32_16x16x32_bf16 v[36:39], v[150:153], v[166:169], v[36:39]
	v_mfma_f32_16x16x32_bf16 v[28:31], v[138:141], v[178:181], v[28:31]
	v_mfma_f32_16x16x32_bf16 v[20:23], v[150:153], v[178:181], v[20:23]
	v_mfma_f32_16x16x32_bf16 v[12:15], v[138:141], v[186:189], v[12:15]
	v_mfma_f32_16x16x32_bf16 v[4:7], v[150:153], v[186:189], v[4:7]
	v_mfma_f32_16x16x32_bf16 v[60:63], v[146:149], v[162:165], v[60:63]
	v_mfma_f32_16x16x32_bf16 v[52:55], v[154:157], v[162:165], v[52:55]
	v_mfma_f32_16x16x32_bf16 v[44:47], v[146:149], v[170:173], v[44:47]
	v_mfma_f32_16x16x32_bf16 v[36:39], v[154:157], v[170:173], v[36:39]
	v_mfma_f32_16x16x32_bf16 v[28:31], v[146:149], v[182:185], v[28:31]
	v_mfma_f32_16x16x32_bf16 v[20:23], v[154:157], v[182:185], v[20:23]
	v_mfma_f32_16x16x32_bf16 v[12:15], v[146:149], v[190:193], v[12:15]
	v_mfma_f32_16x16x32_bf16 v[4:7], v[154:157], v[190:193], v[4:7]
	s_setprio 0
	s_barrier
	s_add_u32 s14, s14, 0x40080
	s_addc_u32 s15, s15, 0
	s_add_i32 s16, s16, s20
	s_mov_b32 m0, s16
	s_nop 0
	global_load_lds_dwordx4 v176, s[14:15]
	s_add_i32 m0, s16, 0x2000
	s_nop 0
	global_load_lds_dwordx4 v128, s[14:15]
	s_waitcnt vmcnt(6)
	s_barrier
	s_setprio 1
	v_mfma_f32_16x16x32_bf16 v[56:59], v[194:197], v[158:161], v[56:59]
	v_mfma_f32_16x16x32_bf16 v[48:51], v[202:205], v[158:161], v[48:51]
	v_mfma_f32_16x16x32_bf16 v[40:43], v[194:197], v[166:169], v[40:43]
	v_mfma_f32_16x16x32_bf16 v[32:35], v[202:205], v[166:169], v[32:35]
	v_mfma_f32_16x16x32_bf16 v[24:27], v[194:197], v[178:181], v[24:27]
	v_mfma_f32_16x16x32_bf16 v[16:19], v[202:205], v[178:181], v[16:19]
	v_mfma_f32_16x16x32_bf16 v[8:11], v[194:197], v[186:189], v[8:11]
	v_mfma_f32_16x16x32_bf16 v[0:3], v[202:205], v[186:189], v[0:3]
	v_mfma_f32_16x16x32_bf16 v[56:59], v[198:201], v[162:165], v[56:59]
	v_mfma_f32_16x16x32_bf16 v[48:51], v[206:209], v[162:165], v[48:51]
	v_mfma_f32_16x16x32_bf16 v[40:43], v[198:201], v[170:173], v[40:43]
	v_mfma_f32_16x16x32_bf16 v[32:35], v[206:209], v[170:173], v[32:35]
	v_mfma_f32_16x16x32_bf16 v[24:27], v[198:201], v[182:185], v[24:27]
	v_mfma_f32_16x16x32_bf16 v[16:19], v[206:209], v[182:185], v[16:19]
	v_mfma_f32_16x16x32_bf16 v[8:11], v[198:201], v[190:193], v[8:11]
	v_mfma_f32_16x16x32_bf16 v[0:3], v[206:209], v[190:193], v[0:3]
	s_setprio 0
	s_add_i32 s45, s45, 2
	s_add_u32 s12, s12, 0x100
	s_addc_u32 s13, s13, 0
	s_add_u32 s43, s43, 0x100
	s_addc_u32 s44, s44, 0
	s_cmp_gt_u32 s45, 13
	s_barrier
	s_cbranch_scc0 .LBB0_114
	v_mul_f32_e32 v147, 0xbfb8aa3b, v124
	v_exp_f32_e32 v147, v147
	v_readlane_b32 s12, v253, 16
	v_lshl_add_u32 v146, s10, 8, v142
	v_lshl_or_b32 v140, s34, 7, v144
	v_add_f32_e32 v147, 1.0, v147
	v_rcp_f32_e32 v150, v147
	v_mul_f32_e32 v147, 0xbfb8aa3b, v125
	v_exp_f32_e32 v147, v147
	v_readlane_b32 s13, v253, 17
	v_ashrrev_i32_e32 v141, 31, v140
	v_lshlrev_b64 v[140:141], 1, v[140:141]
	v_add_f32_e32 v147, 1.0, v147
	v_rcp_f32_e32 v151, v147
	v_mov_b64_e32 v[138:139], s[12:13]
	v_mad_i64_i32 v[148:149], s[12:13], v146, s81, v[138:139]
	v_pk_mul_f32 v[124:125], v[124:125], v[150:151]
	v_lshl_add_u64 v[148:149], v[148:149], 0, v[140:141]
	v_pk_mul_f32 v[120:121], v[124:125], v[120:121]
	s_and_b64 vcc, exec, s[38:39]
	v_cvt_pk_bf16_f32 v120, v120, v121
	v_mul_f32_e32 v121, 0xbfb8aa3b, v126
	v_exp_f32_e32 v121, v121
	s_mov_b32 s34, s0
	s_mov_b32 s10, s4
	s_mov_b64 s[14:15], s[8:9]
	v_add_f32_e32 v121, 1.0, v121
	v_rcp_f32_e32 v124, v121
	v_mul_f32_e32 v121, 0xbfb8aa3b, v127
	v_exp_f32_e32 v121, v121
	s_nop 0
	v_add_f32_e32 v121, 1.0, v121
	v_rcp_f32_e32 v125, v121
	s_nop 0
	v_pk_mul_f32 v[124:125], v[126:127], v[124:125]
	s_nop 0
	v_pk_mul_f32 v[122:123], v[124:125], v[122:123]
	s_nop 0
	v_cvt_pk_bf16_f32 v121, v122, v123
	v_mul_f32_e32 v122, 0xbfb8aa3b, v116
	v_mul_f32_e32 v123, 0xbfb8aa3b, v117
	v_exp_f32_e32 v122, v122
	v_exp_f32_e32 v123, v123
	v_add_f32_e32 v122, 1.0, v122
	v_add_f32_e32 v123, 1.0, v123
	v_rcp_f32_e32 v122, v122
	v_rcp_f32_e32 v123, v123
	s_nop 0
	v_pk_mul_f32 v[116:117], v[116:117], v[122:123]
	s_nop 0
	v_pk_mul_f32 v[112:113], v[116:117], v[112:113]
	s_nop 0
	v_cvt_pk_bf16_f32 v122, v112, v113
	v_mul_f32_e32 v112, 0xbfb8aa3b, v118
	v_mul_f32_e32 v113, 0xbfb8aa3b, v119
	v_exp_f32_e32 v112, v112
	v_exp_f32_e32 v113, v113
	v_add_f32_e32 v112, 1.0, v112
	v_add_f32_e32 v113, 1.0, v113
	v_rcp_f32_e32 v112, v112
	v_rcp_f32_e32 v113, v113
	s_nop 0
	v_pk_mul_f32 v[112:113], v[118:119], v[112:113]
	s_nop 0
	v_pk_mul_f32 v[112:113], v[112:113], v[114:115]
	v_mul_f32_e32 v114, 0xbfb8aa3b, v108
	v_mul_f32_e32 v115, 0xbfb8aa3b, v109
	v_exp_f32_e32 v114, v114
	v_exp_f32_e32 v115, v115
	v_cvt_pk_bf16_f32 v123, v112, v113
	v_or_b32_e32 v112, 16, v146
	v_add_f32_e32 v114, 1.0, v114
	v_add_f32_e32 v115, 1.0, v115
	v_rcp_f32_e32 v114, v114
	v_rcp_f32_e32 v115, v115
	v_mad_i64_i32 v[112:113], s[12:13], v112, s81, v[138:139]
	v_lshl_add_u64 v[112:113], v[112:113], 0, v[140:141]
	v_pk_mul_f32 v[108:109], v[108:109], v[114:115]
	global_store_dwordx4 v[148:149], v[120:123], off
	v_pk_mul_f32 v[104:105], v[108:109], v[104:105]
	s_nop 0
	v_cvt_pk_bf16_f32 v104, v104, v105
	v_mul_f32_e32 v105, 0xbfb8aa3b, v110
	v_exp_f32_e32 v105, v105
	s_nop 0
	v_add_f32_e32 v105, 1.0, v105
	v_rcp_f32_e32 v108, v105
	v_mul_f32_e32 v105, 0xbfb8aa3b, v111
	v_exp_f32_e32 v105, v105
	s_nop 0
	v_add_f32_e32 v105, 1.0, v105
	v_rcp_f32_e32 v109, v105
	s_nop 0
	v_pk_mul_f32 v[108:109], v[110:111], v[108:109]
; __device__ __forceinline__ unsigned cvtpk(float lo, float hi) { const f32x2 v = (f32x2){lo, hi}; const bf16v2 b = __builtin_convertvector(v, bf16v2); return __builtin_bit_cast(unsigned, b); }
; __device__ __forceinline__ float siluf_(float x) { return x * sigmoidf_(x); }
;     __device__ __forceinline__ void operator()(const f32x4 (&acc)[2][2][4][2], const pg8::Unit& u, int wr, int wc, int fr, int fq) const {
;         const int row0 = u.pm * 256 + wr * 64 + fr, col0 = u.pn * 128 + wc * 32 + 8 * fq;
; #pragma unroll
;         for (int ai = 0; ai < 2; ++ai)
; #pragma unroll
;             for (int m = 0; m < 4; ++m) { bf16_t* rowp = O + (size_t)(row0 + ai * 128 + m * 16) * ldc + col0;
;                 const f32x4 g0 = acc[ai][0][m][0], g1 = acc[ai][0][m][1], u0 = acc[ai][1][m][0], u1 = acc[ai][1][m][1];
;                 u32x4 w; w.x = cvtpk(siluf_(g0[0]) * u0[0], siluf_(g0[1]) * u0[1]); w.y = cvtpk(siluf_(g0[2]) * u0[2], siluf_(g0[3]) * u0[3]);
;                 w.z = cvtpk(siluf_(g1[0]) * u1[0], siluf_(g1[1]) * u1[1]); w.w = cvtpk(siluf_(g1[2]) * u1[2], siluf_(g1[3]) * u1[3]);
;                 *(u32x4*)rowp = w; }
;     }
	s_nop 0
	v_pk_mul_f32 v[106:107], v[108:109], v[106:107]
	s_nop 0
	v_cvt_pk_bf16_f32 v105, v106, v107
	v_mul_f32_e32 v106, 0xbfb8aa3b, v100
	v_mul_f32_e32 v107, 0xbfb8aa3b, v101
	v_exp_f32_e32 v106, v106
	v_exp_f32_e32 v107, v107
	v_add_f32_e32 v106, 1.0, v106
	v_add_f32_e32 v107, 1.0, v107
	v_rcp_f32_e32 v106, v106
	v_rcp_f32_e32 v107, v107
	s_nop 0
	v_pk_mul_f32 v[100:101], v[100:101], v[106:107]
	s_nop 0
	v_pk_mul_f32 v[96:97], v[100:101], v[96:97]
	s_nop 0
	v_cvt_pk_bf16_f32 v106, v96, v97
	v_mul_f32_e32 v96, 0xbfb8aa3b, v102
	v_mul_f32_e32 v97, 0xbfb8aa3b, v103
	v_exp_f32_e32 v96, v96
	v_exp_f32_e32 v97, v97
	v_add_f32_e32 v96, 1.0, v96
	v_add_f32_e32 v97, 1.0, v97
	v_rcp_f32_e32 v96, v96
	v_rcp_f32_e32 v97, v97
	s_nop 0
	v_pk_mul_f32 v[96:97], v[102:103], v[96:97]
	s_nop 0
	v_pk_mul_f32 v[96:97], v[96:97], v[98:99]
	v_mul_f32_e32 v98, 0xbfb8aa3b, v92
	v_mul_f32_e32 v99, 0xbfb8aa3b, v93
	v_exp_f32_e32 v98, v98
	v_exp_f32_e32 v99, v99
	v_cvt_pk_bf16_f32 v107, v96, v97
	v_or_b32_e32 v96, 32, v146
	v_add_f32_e32 v98, 1.0, v98
	v_add_f32_e32 v99, 1.0, v99
	v_rcp_f32_e32 v98, v98
	v_rcp_f32_e32 v99, v99
	v_mad_i64_i32 v[96:97], s[12:13], v96, s81, v[138:139]
	v_lshl_add_u64 v[96:97], v[96:97], 0, v[140:141]
	v_pk_mul_f32 v[92:93], v[92:93], v[98:99]
	global_store_dwordx4 v[112:113], v[104:107], off
	v_pk_mul_f32 v[88:89], v[92:93], v[88:89]
	s_nop 0
	v_cvt_pk_bf16_f32 v88, v88, v89
	v_mul_f32_e32 v89, 0xbfb8aa3b, v94
	v_exp_f32_e32 v89, v89
	s_nop 0
	v_add_f32_e32 v89, 1.0, v89
	v_rcp_f32_e32 v92, v89
	v_mul_f32_e32 v89, 0xbfb8aa3b, v95
	v_exp_f32_e32 v89, v89
	s_nop 0
	v_add_f32_e32 v89, 1.0, v89
	v_rcp_f32_e32 v93, v89
	s_nop 0
	v_pk_mul_f32 v[92:93], v[94:95], v[92:93]
	s_nop 0
	v_pk_mul_f32 v[90:91], v[92:93], v[90:91]
	s_nop 0
	v_cvt_pk_bf16_f32 v89, v90, v91
	v_mul_f32_e32 v90, 0xbfb8aa3b, v84
	v_mul_f32_e32 v91, 0xbfb8aa3b, v85
	v_exp_f32_e32 v90, v90
	v_exp_f32_e32 v91, v91
	v_add_f32_e32 v90, 1.0, v90
	v_add_f32_e32 v91, 1.0, v91
	v_rcp_f32_e32 v90, v90
	v_rcp_f32_e32 v91, v91
	s_nop 0
	v_pk_mul_f32 v[84:85], v[84:85], v[90:91]
	s_nop 0
	v_pk_mul_f32 v[80:81], v[84:85], v[80:81]
	s_nop 0
	v_cvt_pk_bf16_f32 v90, v80, v81
	v_mul_f32_e32 v80, 0xbfb8aa3b, v86
	v_mul_f32_e32 v81, 0xbfb8aa3b, v87
	v_exp_f32_e32 v80, v80
	v_exp_f32_e32 v81, v81
	v_add_f32_e32 v80, 1.0, v80
	v_add_f32_e32 v81, 1.0, v81
	v_rcp_f32_e32 v80, v80
	v_rcp_f32_e32 v81, v81
	s_nop 0
	v_pk_mul_f32 v[80:81], v[86:87], v[80:81]
	s_nop 0
	v_pk_mul_f32 v[80:81], v[80:81], v[82:83]
	v_mul_f32_e32 v82, 0xbfb8aa3b, v76
	v_mul_f32_e32 v83, 0xbfb8aa3b, v77
	v_exp_f32_e32 v82, v82
	v_exp_f32_e32 v83, v83
	v_cvt_pk_bf16_f32 v91, v80, v81
	v_or_b32_e32 v80, 48, v146
	v_add_f32_e32 v82, 1.0, v82
	v_add_f32_e32 v83, 1.0, v83
	v_rcp_f32_e32 v82, v82
	v_rcp_f32_e32 v83, v83
	v_mad_i64_i32 v[80:81], s[12:13], v80, s81, v[138:139]
	v_lshl_add_u64 v[80:81], v[80:81], 0, v[140:141]
	v_pk_mul_f32 v[76:77], v[76:77], v[82:83]
	global_store_dwordx4 v[96:97], v[88:91], off
	v_pk_mul_f32 v[72:73], v[76:77], v[72:73]
	s_nop 0
	v_cvt_pk_bf16_f32 v72, v72, v73
	v_mul_f32_e32 v73, 0xbfb8aa3b, v78
	v_exp_f32_e32 v73, v73
	s_nop 0
	v_add_f32_e32 v73, 1.0, v73
	v_rcp_f32_e32 v76, v73
	v_mul_f32_e32 v73, 0xbfb8aa3b, v79
	v_exp_f32_e32 v73, v73
	s_nop 0
	v_add_f32_e32 v73, 1.0, v73
	v_rcp_f32_e32 v77, v73
	s_nop 0
	v_pk_mul_f32 v[76:77], v[78:79], v[76:77]
	s_nop 0
	v_pk_mul_f32 v[74:75], v[76:77], v[74:75]
	s_nop 0
	v_cvt_pk_bf16_f32 v73, v74, v75
	v_mul_f32_e32 v74, 0xbfb8aa3b, v68
	v_mul_f32_e32 v75, 0xbfb8aa3b, v69
	v_exp_f32_e32 v74, v74
	v_exp_f32_e32 v75, v75
	v_add_f32_e32 v74, 1.0, v74
	v_add_f32_e32 v75, 1.0, v75
	v_rcp_f32_e32 v74, v74
	v_rcp_f32_e32 v75, v75
	s_nop 0
	v_pk_mul_f32 v[68:69], v[68:69], v[74:75]
	s_nop 0
	v_pk_mul_f32 v[64:65], v[68:69], v[64:65]
	s_nop 0
	v_cvt_pk_bf16_f32 v74, v64, v65
	v_mul_f32_e32 v64, 0xbfb8aa3b, v70
	v_mul_f32_e32 v65, 0xbfb8aa3b, v71
	v_exp_f32_e32 v64, v64
	v_exp_f32_e32 v65, v65
	v_add_f32_e32 v64, 1.0, v64
	v_add_f32_e32 v65, 1.0, v65
	v_rcp_f32_e32 v64, v64
	v_rcp_f32_e32 v65, v65
	s_nop 0
	v_pk_mul_f32 v[64:65], v[70:71], v[64:65]
	s_nop 0
	v_pk_mul_f32 v[64:65], v[64:65], v[66:67]
	v_mul_f32_e32 v66, 0xbfb8aa3b, v60
	v_mul_f32_e32 v67, 0xbfb8aa3b, v61
	v_exp_f32_e32 v66, v66
	v_exp_f32_e32 v67, v67
	v_cvt_pk_bf16_f32 v75, v64, v65
	v_add_u32_e32 v64, 0x80, v146
	v_add_f32_e32 v66, 1.0, v66
	v_add_f32_e32 v67, 1.0, v67
	v_rcp_f32_e32 v66, v66
	v_rcp_f32_e32 v67, v67
	v_mad_i64_i32 v[64:65], s[12:13], v64, s81, v[138:139]
	v_lshl_add_u64 v[64:65], v[64:65], 0, v[140:141]
	v_pk_mul_f32 v[60:61], v[60:61], v[66:67]
	global_store_dwordx4 v[80:81], v[72:75], off
	v_pk_mul_f32 v[56:57], v[60:61], v[56:57]
	s_nop 0
	v_cvt_pk_bf16_f32 v56, v56, v57
	v_mul_f32_e32 v57, 0xbfb8aa3b, v62
	v_exp_f32_e32 v57, v57
	s_nop 0
	v_add_f32_e32 v57, 1.0, v57
	v_rcp_f32_e32 v60, v57
	v_mul_f32_e32 v57, 0xbfb8aa3b, v63
	v_exp_f32_e32 v57, v57
	s_nop 0
	v_add_f32_e32 v57, 1.0, v57
	v_rcp_f32_e32 v61, v57
	s_nop 0
	v_pk_mul_f32 v[60:61], v[62:63], v[60:61]
	s_nop 0
	v_pk_mul_f32 v[58:59], v[60:61], v[58:59]
	s_nop 0
	v_cvt_pk_bf16_f32 v57, v58, v59
	v_mul_f32_e32 v58, 0xbfb8aa3b, v52
	v_mul_f32_e32 v59, 0xbfb8aa3b, v53
	v_exp_f32_e32 v58, v58
	v_exp_f32_e32 v59, v59
	v_add_f32_e32 v58, 1.0, v58
	v_add_f32_e32 v59, 1.0, v59
	v_rcp_f32_e32 v58, v58
	v_rcp_f32_e32 v59, v59
	s_nop 0
	v_pk_mul_f32 v[52:53], v[52:53], v[58:59]
	s_nop 0
	v_pk_mul_f32 v[48:49], v[52:53], v[48:49]
	s_nop 0
	v_cvt_pk_bf16_f32 v58, v48, v49
	v_mul_f32_e32 v48, 0xbfb8aa3b, v54
; __device__ __forceinline__ unsigned cvtpk(float lo, float hi) { const f32x2 v = (f32x2){lo, hi}; const bf16v2 b = __builtin_convertvector(v, bf16v2); return __builtin_bit_cast(unsigned, b); }
; __device__ __forceinline__ float siluf_(float x) { return x * sigmoidf_(x); }
; #define PG8_WAIT_V(n) asm volatile("s_waitcnt vmcnt(" #n ")" ::: "memory")
; #define PG8_BAR __builtin_amdgcn_s_barrier()
; template <class Epi, class Sched>
; __device__ __forceinline__ void gemm_phase(PG8_LAS unsigned char* lds, const Gemm g, const Sched& S, const Epi& E) {
;     ...
;         if constexpr (!Epi::AFTER_DRAIN) { E(acc, cur, wr, wc, fr, fq); S.done(cur); }
;         if (!has_next) break;
; #pragma unroll
;         for (int a = 0; a < 2; ++a)
; #pragma unroll
;             for (int b = 0; b < 2; ++b)
; #pragma unroll
;                 for (int m = 0; m < 4; ++m)
; #pragma unroll
;                     for (int n = 0; n < 2; ++n) acc[a][b][m][n] = (f32x4){0.f, 0.f, 0.f, 0.f};
;         cur = nxt; cA = nA; cB = nB; ++ui;
;     }
;     PG8_WAIT_V(0);
;     if (wr == 0) PG8_BAR;
;     __device__ __forceinline__ void operator()(const f32x4 (&acc)[2][2][4][2], const pg8::Unit& u, int wr, int wc, int fr, int fq) const {
;         const int row0 = u.pm * 256 + wr * 64 + fr, col0 = u.pn * 128 + wc * 32 + 8 * fq;
; #pragma unroll
;         for (int ai = 0; ai < 2; ++ai)
; #pragma unroll
;             for (int m = 0; m < 4; ++m) { bf16_t* rowp = O + (size_t)(row0 + ai * 128 + m * 16) * ldc + col0;
;                 const f32x4 g0 = acc[ai][0][m][0], g1 = acc[ai][0][m][1], u0 = acc[ai][1][m][0], u1 = acc[ai][1][m][1];
;                 u32x4 w; w.x = cvtpk(siluf_(g0[0]) * u0[0], siluf_(g0[1]) * u0[1]); w.y = cvtpk(siluf_(g0[2]) * u0[2], siluf_(g0[3]) * u0[3]);
;                 w.z = cvtpk(siluf_(g1[0]) * u1[0], siluf_(g1[1]) * u1[1]); w.w = cvtpk(siluf_(g1[2]) * u1[2], siluf_(g1[3]) * u1[3]);
;                 *(u32x4*)rowp = w; }
;     }
	v_mul_f32_e32 v49, 0xbfb8aa3b, v55
	v_exp_f32_e32 v48, v48
	v_exp_f32_e32 v49, v49
	v_add_f32_e32 v48, 1.0, v48
	v_add_f32_e32 v49, 1.0, v49
	v_rcp_f32_e32 v48, v48
	v_rcp_f32_e32 v49, v49
	s_nop 0
	v_pk_mul_f32 v[48:49], v[54:55], v[48:49]
	s_nop 0
	v_pk_mul_f32 v[48:49], v[48:49], v[50:51]
	v_mul_f32_e32 v50, 0xbfb8aa3b, v44
	v_mul_f32_e32 v51, 0xbfb8aa3b, v45
	v_exp_f32_e32 v50, v50
	v_exp_f32_e32 v51, v51
	v_cvt_pk_bf16_f32 v59, v48, v49
	v_add_u32_e32 v48, 0x90, v146
	v_add_f32_e32 v50, 1.0, v50
	v_add_f32_e32 v51, 1.0, v51
	v_rcp_f32_e32 v50, v50
	v_rcp_f32_e32 v51, v51
	v_mad_i64_i32 v[48:49], s[12:13], v48, s81, v[138:139]
	v_lshl_add_u64 v[48:49], v[48:49], 0, v[140:141]
	v_pk_mul_f32 v[44:45], v[44:45], v[50:51]
	global_store_dwordx4 v[64:65], v[56:59], off
	v_pk_mul_f32 v[40:41], v[44:45], v[40:41]
	s_nop 0
	v_cvt_pk_bf16_f32 v40, v40, v41
	v_mul_f32_e32 v41, 0xbfb8aa3b, v46
	v_exp_f32_e32 v41, v41
	s_nop 0
	v_add_f32_e32 v41, 1.0, v41
	v_rcp_f32_e32 v44, v41
	v_mul_f32_e32 v41, 0xbfb8aa3b, v47
	v_exp_f32_e32 v41, v41
	s_nop 0
	v_add_f32_e32 v41, 1.0, v41
	v_rcp_f32_e32 v45, v41
	s_nop 0
	v_pk_mul_f32 v[44:45], v[46:47], v[44:45]
	s_nop 0
	v_pk_mul_f32 v[42:43], v[44:45], v[42:43]
	s_nop 0
	v_cvt_pk_bf16_f32 v41, v42, v43
	v_mul_f32_e32 v42, 0xbfb8aa3b, v36
	v_mul_f32_e32 v43, 0xbfb8aa3b, v37
	v_exp_f32_e32 v42, v42
	v_exp_f32_e32 v43, v43
	v_add_f32_e32 v42, 1.0, v42
	v_add_f32_e32 v43, 1.0, v43
	v_rcp_f32_e32 v42, v42
	v_rcp_f32_e32 v43, v43
	s_nop 0
	v_pk_mul_f32 v[36:37], v[36:37], v[42:43]
	s_nop 0
	v_pk_mul_f32 v[32:33], v[36:37], v[32:33]
	s_nop 0
	v_cvt_pk_bf16_f32 v42, v32, v33
	v_mul_f32_e32 v32, 0xbfb8aa3b, v38
	v_mul_f32_e32 v33, 0xbfb8aa3b, v39
	v_exp_f32_e32 v32, v32
	v_exp_f32_e32 v33, v33
	v_add_f32_e32 v32, 1.0, v32
	v_add_f32_e32 v33, 1.0, v33
	v_rcp_f32_e32 v32, v32
	v_rcp_f32_e32 v33, v33
	s_nop 0
	v_pk_mul_f32 v[32:33], v[38:39], v[32:33]
	s_nop 0
	v_pk_mul_f32 v[32:33], v[32:33], v[34:35]
	v_mul_f32_e32 v34, 0xbfb8aa3b, v28
	v_mul_f32_e32 v35, 0xbfb8aa3b, v29
	v_exp_f32_e32 v34, v34
	v_exp_f32_e32 v35, v35
	v_cvt_pk_bf16_f32 v43, v32, v33
	v_add_u32_e32 v32, 0xa0, v146
	v_add_f32_e32 v34, 1.0, v34
	v_add_f32_e32 v35, 1.0, v35
	v_rcp_f32_e32 v34, v34
	v_rcp_f32_e32 v35, v35
	v_mad_i64_i32 v[32:33], s[12:13], v32, s81, v[138:139]
	v_lshl_add_u64 v[32:33], v[32:33], 0, v[140:141]
	v_pk_mul_f32 v[28:29], v[28:29], v[34:35]
	global_store_dwordx4 v[48:49], v[40:43], off
	v_pk_mul_f32 v[24:25], v[28:29], v[24:25]
	s_nop 0
	v_cvt_pk_bf16_f32 v24, v24, v25
	v_mul_f32_e32 v25, 0xbfb8aa3b, v30
	v_exp_f32_e32 v25, v25
	s_nop 0
	v_add_f32_e32 v25, 1.0, v25
	v_rcp_f32_e32 v28, v25
	v_mul_f32_e32 v25, 0xbfb8aa3b, v31
	v_exp_f32_e32 v25, v25
	s_nop 0
	v_add_f32_e32 v25, 1.0, v25
	v_rcp_f32_e32 v29, v25
	s_nop 0
	v_pk_mul_f32 v[28:29], v[30:31], v[28:29]
	s_nop 0
	v_pk_mul_f32 v[26:27], v[28:29], v[26:27]
	s_nop 0
	v_cvt_pk_bf16_f32 v25, v26, v27
	v_mul_f32_e32 v26, 0xbfb8aa3b, v20
	v_mul_f32_e32 v27, 0xbfb8aa3b, v21
	v_exp_f32_e32 v26, v26
	v_exp_f32_e32 v27, v27
	v_add_f32_e32 v26, 1.0, v26
	v_add_f32_e32 v27, 1.0, v27
	v_rcp_f32_e32 v26, v26
	v_rcp_f32_e32 v27, v27
	s_nop 0
	v_pk_mul_f32 v[20:21], v[20:21], v[26:27]
	s_nop 0
	v_pk_mul_f32 v[16:17], v[20:21], v[16:17]
	s_nop 0
	v_cvt_pk_bf16_f32 v26, v16, v17
	v_mul_f32_e32 v16, 0xbfb8aa3b, v22
	v_mul_f32_e32 v17, 0xbfb8aa3b, v23
	v_exp_f32_e32 v16, v16
	v_exp_f32_e32 v17, v17
	v_add_f32_e32 v16, 1.0, v16
	v_add_f32_e32 v17, 1.0, v17
	v_rcp_f32_e32 v16, v16
	v_rcp_f32_e32 v17, v17
	s_nop 0
	v_pk_mul_f32 v[16:17], v[22:23], v[16:17]
	s_nop 0
	v_pk_mul_f32 v[16:17], v[16:17], v[18:19]
	v_mul_f32_e32 v18, 0xbfb8aa3b, v12
	v_mul_f32_e32 v19, 0xbfb8aa3b, v13
	v_exp_f32_e32 v18, v18
	v_exp_f32_e32 v19, v19
	v_cvt_pk_bf16_f32 v27, v16, v17
	v_add_u32_e32 v16, 0xb0, v146
	v_add_f32_e32 v18, 1.0, v18
	v_add_f32_e32 v19, 1.0, v19
	v_rcp_f32_e32 v18, v18
	v_rcp_f32_e32 v19, v19
	v_mad_i64_i32 v[16:17], s[12:13], v16, s81, v[138:139]
	v_lshl_add_u64 v[16:17], v[16:17], 0, v[140:141]
	v_pk_mul_f32 v[12:13], v[12:13], v[18:19]
	s_mov_b64 s[12:13], s[6:7]
	v_pk_mul_f32 v[8:9], v[12:13], v[8:9]
	global_store_dwordx4 v[32:33], v[24:27], off
	v_cvt_pk_bf16_f32 v8, v8, v9
	v_mul_f32_e32 v9, 0xbfb8aa3b, v14
	v_exp_f32_e32 v9, v9
	s_nop 0
	v_add_f32_e32 v9, 1.0, v9
	v_rcp_f32_e32 v12, v9
	v_mul_f32_e32 v9, 0xbfb8aa3b, v15
	v_exp_f32_e32 v9, v9
	s_nop 0
	v_add_f32_e32 v9, 1.0, v9
	v_rcp_f32_e32 v13, v9
	s_nop 0
	v_pk_mul_f32 v[12:13], v[14:15], v[12:13]
	s_nop 0
	v_pk_mul_f32 v[10:11], v[12:13], v[10:11]
	s_nop 0
	v_cvt_pk_bf16_f32 v9, v10, v11
	v_mul_f32_e32 v10, 0xbfb8aa3b, v4
	v_mul_f32_e32 v11, 0xbfb8aa3b, v5
	v_exp_f32_e32 v10, v10
	v_exp_f32_e32 v11, v11
	v_add_f32_e32 v10, 1.0, v10
	v_add_f32_e32 v11, 1.0, v11
	v_rcp_f32_e32 v10, v10
	v_rcp_f32_e32 v11, v11
	s_nop 0
	v_pk_mul_f32 v[4:5], v[4:5], v[10:11]
	s_nop 0
	v_pk_mul_f32 v[0:1], v[4:5], v[0:1]
	s_nop 0
	v_cvt_pk_bf16_f32 v10, v0, v1
	v_mul_f32_e32 v0, 0xbfb8aa3b, v6
	v_mul_f32_e32 v1, 0xbfb8aa3b, v7
	v_exp_f32_e32 v0, v0
	v_exp_f32_e32 v1, v1
	v_add_f32_e32 v0, 1.0, v0
	v_add_f32_e32 v1, 1.0, v1
	v_rcp_f32_e32 v0, v0
	v_rcp_f32_e32 v1, v1
	s_nop 0
	v_pk_mul_f32 v[0:1], v[6:7], v[0:1]
	s_nop 0
	v_pk_mul_f32 v[0:1], v[0:1], v[2:3]
	s_nop 0
	v_cvt_pk_bf16_f32 v11, v0, v1
	global_store_dwordx4 v[16:17], v[8:11], off
	s_cbranch_vccz .LBB0_111
	s_waitcnt vmcnt(0)
	v_readlane_b32 s22, v255, 14
	s_cmpk_gt_u32 s19, 0xff
	v_readlane_b32 s23, v255, 15
	s_mov_b64 s[28:29], s[54:55]
	s_cbranch_scc1 .LBB0_118
	s_barrier

; #define PG8_STAGE(bufoff, gbase, voff) do { _Pragma("unroll") for (int _i = 0; _i < 2; ++_i) \
;         __builtin_amdgcn_global_load_lds((const unsigned*)((const char*)(gbase) + (voff)[_i]), (PG8_LAS unsigned*)(lds + (bufoff) + ldsw + _i * 8192), 16, 0, 0); } while (0)
; #define PG8_LDA(dst, b, h) do { _Pragma("unroll") for (int m = 0; m < 4; ++m) _Pragma("unroll") for (int k = 0; k < 2; ++k) dst[m][k] = *(const PG8_LAS bf16x8*)(lds + PG8_SA(b, h) + aoff + m * 2048 + k * 1024); } while (0)
; #define PG8_LDB(dst, b, h) do { _Pragma("unroll") for (int n = 0; n < 2; ++n) _Pragma("unroll") for (int k = 0; k < 2; ++k) dst[n][k] = *(const PG8_LAS bf16x8*)(lds + PG8_SB(b, h) + boff + n * 2048 + k * 1024); } while (0)
; #define PG8_MMA(ai, bj, At, Bt) do { __builtin_amdgcn_s_setprio(1); _Pragma("unroll") for (int m = 0; m < 4; ++m) _Pragma("unroll") for (int n = 0; n < 2; ++n) _Pragma("unroll") for (int k = 0; k < 2; ++k) \
;         acc[ai][bj][m][n] = __builtin_amdgcn_mfma_f32_16x16x32_bf16(Bt[n][k], At[m][k], acc[ai][bj][m][n], 0, 0, 0); __builtin_amdgcn_s_setprio(0); } while (0)
; #define PG8_WAIT_V(n) asm volatile("s_waitcnt vmcnt(" #n ")" ::: "memory")
; template <class Epi, class Sched>
; __device__ __forceinline__ void gemm_phase(PG8_LAS unsigned char* lds, const Gemm g, const Sched& S, const Epi& E) {
;     ...
;         for (int t = 0; t < nt; t += 2) {
;             const bool last = (t == nt - 2);
;             const char* a1 = cA + (size_t)(t + 1) * kstep;
;             const char* a2 = last ? nA : cA + (size_t)(t + 2) * kstep; const char* b2 = last ? nB : cB + (size_t)(t + 2) * kstep;
;             const char* a3 = a2 + kstep; const char* b3 = b2 + kstep;
;             if (last && has_next) S.a_ready(nxt);
;             PG8_LDB(B0, 0, 0); PG8_SCHED; PG8_LDA(At, 0, 0); PG8_STAGE(PG8_SA(1, 1), a1 + hstep, voffA);
;             PG8_WAIT_L(8); PG8_BAR; PG8_WAIT_L(0); PG8_MMA(0, 0, At, B0); PG8_BAR; PG8_SCHED;
;             PG8_LDB(B1, 0, 1); PG8_STAGE(PG8_SB(0, 0), b2, voffB);
;             PG8_BAR; PG8_WAIT_L(0); PG8_MMA(0, 1, At, B1); PG8_BAR;
;             PG8_LDA(At, 0, 1); PG8_STAGE(PG8_SA(0, 0), a2, voffA);
;             PG8_BAR; PG8_WAIT_L(0); PG8_MMA(1, 0, At, B0); PG8_BAR; PG8_SCHED;
;             PG8_STAGE(PG8_SB(0, 1), b2 + hstep, voffB);
;             PG8_WAIT_V(6); PG8_BAR; PG8_MMA(1, 1, At, B1); PG8_BAR;
.LBB0_137:
	s_add_u32 s14, s12, 0xfffc0080
	s_addc_u32 s15, s13, -1
	s_add_i32 s46, 0, 0x10000
	v_add_u32_e32 v154, s46, v139
	ds_read_b128 v[142:145], v154
	ds_read_b128 v[146:149], v154 offset:1024
	ds_read_b128 v[150:153], v154 offset:2048
	ds_read_b128 v[154:157], v154 offset:3072
	s_cmp_eq_u32 s45, 12
	s_cselect_b32 s17, s7, s15
	s_cselect_b32 s16, s40, s14
	s_cselect_b32 s15, s5, s44
	s_cselect_b32 s14, s41, s43
	s_add_i32 m0, s1, 0xc000
	ds_read_b128 v[158:161], v141
	ds_read_b128 v[162:165], v141 offset:1024
	ds_read_b128 v[166:169], v141 offset:2048
	ds_read_b128 v[170:173], v141 offset:3072
	ds_read_b128 v[178:181], v141 offset:4096
	ds_read_b128 v[182:185], v141 offset:5120
	ds_read_b128 v[186:189], v141 offset:6144
	ds_read_b128 v[190:193], v141 offset:7168
	global_load_lds_dwordx4 v134, s[12:13]
	s_add_i32 m0, s1, 0xe000
	s_nop 0
	global_load_lds_dwordx4 v136, s[12:13]
	s_waitcnt lgkmcnt(8)
	s_barrier
	s_waitcnt lgkmcnt(0)
	s_setprio 1
	v_mfma_f32_16x16x32_bf16 v[124:127], v[142:145], v[158:161], v[124:127]
	v_mfma_f32_16x16x32_bf16 v[120:123], v[150:153], v[158:161], v[120:123]
	v_mfma_f32_16x16x32_bf16 v[116:119], v[142:145], v[166:169], v[116:119]
	v_mfma_f32_16x16x32_bf16 v[112:115], v[150:153], v[166:169], v[112:115]
	v_mfma_f32_16x16x32_bf16 v[100:103], v[142:145], v[178:181], v[100:103]
	v_mfma_f32_16x16x32_bf16 v[96:99], v[150:153], v[178:181], v[96:99]
	v_mfma_f32_16x16x32_bf16 v[84:87], v[142:145], v[186:189], v[84:87]
	v_mfma_f32_16x16x32_bf16 v[80:83], v[150:153], v[186:189], v[80:83]
	v_mfma_f32_16x16x32_bf16 v[124:127], v[146:149], v[162:165], v[124:127]
	v_mfma_f32_16x16x32_bf16 v[120:123], v[154:157], v[162:165], v[120:123]
	v_mfma_f32_16x16x32_bf16 v[116:119], v[146:149], v[170:173], v[116:119]
	v_mfma_f32_16x16x32_bf16 v[112:115], v[154:157], v[170:173], v[112:115]
	v_mfma_f32_16x16x32_bf16 v[100:103], v[146:149], v[182:185], v[100:103]
	v_mfma_f32_16x16x32_bf16 v[96:99], v[154:157], v[182:185], v[96:99]
	v_mfma_f32_16x16x32_bf16 v[84:87], v[146:149], v[190:193], v[84:87]
	v_mfma_f32_16x16x32_bf16 v[80:83], v[154:157], v[190:193], v[80:83]
	s_setprio 0
	s_barrier
	s_add_i32 s48, 0, 0x14000
	v_add_u32_e32 v174, s48, v139
	s_add_i32 s46, s46, s20
	ds_read_b128 v[194:197], v174
	ds_read_b128 v[198:201], v174 offset:1024
	ds_read_b128 v[202:205], v174 offset:2048
	ds_read_b128 v[206:209], v174 offset:3072
	s_add_u32 s98, s14, 0x80
	s_addc_u32 s99, s15, 0
	s_mov_b32 m0, s46
	s_nop 0
	global_load_lds_dwordx4 v176, s[14:15]
	s_add_i32 m0, s46, 0x2000
	s_nop 0
	global_load_lds_dwordx4 v128, s[14:15]
	s_barrier
	s_waitcnt lgkmcnt(0)
	s_setprio 1
	v_mfma_f32_16x16x32_bf16 v[108:111], v[194:197], v[158:161], v[108:111]
	v_mfma_f32_16x16x32_bf16 v[104:107], v[202:205], v[158:161], v[104:107]
	v_mfma_f32_16x16x32_bf16 v[92:95], v[194:197], v[166:169], v[92:95]
	v_mfma_f32_16x16x32_bf16 v[88:91], v[202:205], v[166:169], v[88:91]
	v_mfma_f32_16x16x32_bf16 v[76:79], v[194:197], v[178:181], v[76:79]
	v_mfma_f32_16x16x32_bf16 v[72:75], v[202:205], v[178:181], v[72:75]
	v_mfma_f32_16x16x32_bf16 v[68:71], v[194:197], v[186:189], v[68:71]
	v_mfma_f32_16x16x32_bf16 v[64:67], v[202:205], v[186:189], v[64:67]
	v_mfma_f32_16x16x32_bf16 v[108:111], v[198:201], v[162:165], v[108:111]
	v_mfma_f32_16x16x32_bf16 v[104:107], v[206:209], v[162:165], v[104:107]
	v_mfma_f32_16x16x32_bf16 v[92:95], v[198:201], v[170:173], v[92:95]
	v_mfma_f32_16x16x32_bf16 v[88:91], v[206:209], v[170:173], v[88:91]
	v_mfma_f32_16x16x32_bf16 v[76:79], v[198:201], v[182:185], v[76:79]
	v_mfma_f32_16x16x32_bf16 v[72:75], v[206:209], v[182:185], v[72:75]
	v_mfma_f32_16x16x32_bf16 v[68:71], v[198:201], v[190:193], v[68:71]
	v_mfma_f32_16x16x32_bf16 v[64:67], v[206:209], v[190:193], v[64:67]
	s_setprio 0
	s_mov_b32 m0, s1
	s_add_u32 s100, s16, 0x80
	s_addc_u32 s101, s17, 0
	s_barrier
	ds_read_b128 v[158:161], v141 offset:16384
	ds_read_b128 v[162:165], v141 offset:17408
	ds_read_b128 v[166:169], v141 offset:18432
	ds_read_b128 v[170:173], v141 offset:19456
	ds_read_b128 v[178:181], v141 offset:20480
	ds_read_b128 v[182:185], v141 offset:21504
	ds_read_b128 v[186:189], v141 offset:22528
	ds_read_b128 v[190:193], v141 offset:23552
	global_load_lds_dwordx4 v132, s[16:17]
	s_mov_b32 m0, s22
	s_nop 0
	global_load_lds_dwordx4 v130, s[16:17]
	s_barrier
	s_waitcnt lgkmcnt(0)
	s_setprio 1
	v_mfma_f32_16x16x32_bf16 v[60:63], v[142:145], v[158:161], v[60:63]
	v_mfma_f32_16x16x32_bf16 v[56:59], v[150:153], v[158:161], v[56:59]
	v_mfma_f32_16x16x32_bf16 v[52:55], v[142:145], v[166:169], v[52:55]
	v_mfma_f32_16x16x32_bf16 v[48:51], v[150:153], v[166:169], v[48:51]
	v_mfma_f32_16x16x32_bf16 v[36:39], v[142:145], v[178:181], v[36:39]
	v_mfma_f32_16x16x32_bf16 v[32:35], v[150:153], v[178:181], v[32:35]
	v_mfma_f32_16x16x32_bf16 v[20:23], v[142:145], v[186:189], v[20:23]
	v_mfma_f32_16x16x32_bf16 v[16:19], v[150:153], v[186:189], v[16:19]
	v_mfma_f32_16x16x32_bf16 v[60:63], v[146:149], v[162:165], v[60:63]
	v_mfma_f32_16x16x32_bf16 v[56:59], v[154:157], v[162:165], v[56:59]
	v_mfma_f32_16x16x32_bf16 v[52:55], v[146:149], v[170:173], v[52:55]
	v_mfma_f32_16x16x32_bf16 v[48:51], v[154:157], v[170:173], v[48:51]
	v_mfma_f32_16x16x32_bf16 v[36:39], v[146:149], v[182:185], v[36:39]
	v_mfma_f32_16x16x32_bf16 v[32:35], v[154:157], v[182:185], v[32:35]
	v_mfma_f32_16x16x32_bf16 v[20:23], v[146:149], v[190:193], v[20:23]
	v_mfma_f32_16x16x32_bf16 v[16:19], v[154:157], v[190:193], v[16:19]
	s_setprio 0
	s_barrier
	s_add_u32 s46, s14, 0x40000
	s_addc_u32 s47, s15, 0
	s_add_i32 s48, s48, s20
	s_mov_b32 m0, s48
	s_nop 0
	global_load_lds_dwordx4 v176, s[46:47]
	s_add_i32 m0, s48, 0x2000
	s_nop 0
	global_load_lds_dwordx4 v128, s[46:47]
	s_waitcnt vmcnt(6)
	s_barrier
; #define PG8_STAGE(bufoff, gbase, voff) do { _Pragma("unroll") for (int _i = 0; _i < 2; ++_i) \
;         __builtin_amdgcn_global_load_lds((const unsigned*)((const char*)(gbase) + (voff)[_i]), (PG8_LAS unsigned*)(lds + (bufoff) + ldsw + _i * 8192), 16, 0, 0); } while (0)
; #define PG8_LDA(dst, b, h) do { _Pragma("unroll") for (int m = 0; m < 4; ++m) _Pragma("unroll") for (int k = 0; k < 2; ++k) dst[m][k] = *(const PG8_LAS bf16x8*)(lds + PG8_SA(b, h) + aoff + m * 2048 + k * 1024); } while (0)
; #define PG8_LDB(dst, b, h) do { _Pragma("unroll") for (int n = 0; n < 2; ++n) _Pragma("unroll") for (int k = 0; k < 2; ++k) dst[n][k] = *(const PG8_LAS bf16x8*)(lds + PG8_SB(b, h) + boff + n * 2048 + k * 1024); } while (0)
; #define PG8_MMA(ai, bj, At, Bt) do { __builtin_amdgcn_s_setprio(1); _Pragma("unroll") for (int m = 0; m < 4; ++m) _Pragma("unroll") for (int n = 0; n < 2; ++n) _Pragma("unroll") for (int k = 0; k < 2; ++k) \
;         acc[ai][bj][m][n] = __builtin_amdgcn_mfma_f32_16x16x32_bf16(Bt[n][k], At[m][k], acc[ai][bj][m][n], 0, 0, 0); __builtin_amdgcn_s_setprio(0); } while (0)
; #define PG8_WAIT_V(n) asm volatile("s_waitcnt vmcnt(" #n ")" ::: "memory")
; #define PG8_WAIT_L(n) asm volatile("s_waitcnt lgkmcnt(" #n ")" ::: "memory")
; #define PG8_BAR __builtin_amdgcn_s_barrier()
; #define PG8_SCHED __builtin_amdgcn_sched_barrier(0)
; template <class Epi, class Sched>
; __device__ __forceinline__ void gemm_phase(PG8_LAS unsigned char* lds, const Gemm g, const Sched& S, const Epi& E) {
;     ...
;             PG8_WAIT_V(6); PG8_BAR; PG8_MMA(1, 1, At, B1); PG8_BAR;
;             PG8_LDB(B0, 1, 0); PG8_SCHED; PG8_LDA(At, 1, 0); PG8_STAGE(PG8_SA(0, 1), a2 + hstep, voffA);
;             PG8_WAIT_L(8); PG8_BAR; PG8_WAIT_L(0); PG8_MMA(0, 0, At, B0); PG8_BAR; PG8_SCHED;
;             PG8_LDB(B1, 1, 1); PG8_STAGE(PG8_SB(1, 0), b3, voffB);
;             PG8_BAR; PG8_WAIT_L(0); PG8_MMA(0, 1, At, B1); PG8_BAR;
;             PG8_LDA(At, 1, 1); PG8_STAGE(PG8_SA(1, 0), a3, voffA);
;             PG8_BAR; PG8_WAIT_L(0); PG8_MMA(1, 0, At, B0); PG8_BAR; PG8_SCHED;
	s_setprio 1
	v_mfma_f32_16x16x32_bf16 v[44:47], v[194:197], v[158:161], v[44:47]
	v_mfma_f32_16x16x32_bf16 v[40:43], v[202:205], v[158:161], v[40:43]
	v_mfma_f32_16x16x32_bf16 v[28:31], v[194:197], v[166:169], v[28:31]
	v_mfma_f32_16x16x32_bf16 v[24:27], v[202:205], v[166:169], v[24:27]
	v_mfma_f32_16x16x32_bf16 v[12:15], v[194:197], v[178:181], v[12:15]
	v_mfma_f32_16x16x32_bf16 v[8:11], v[202:205], v[178:181], v[8:11]
	v_mfma_f32_16x16x32_bf16 v[4:7], v[194:197], v[186:189], v[4:7]
	v_mfma_f32_16x16x32_bf16 v[0:3], v[202:205], v[186:189], v[0:3]
	v_mfma_f32_16x16x32_bf16 v[44:47], v[198:201], v[162:165], v[44:47]
	v_mfma_f32_16x16x32_bf16 v[40:43], v[206:209], v[162:165], v[40:43]
	v_mfma_f32_16x16x32_bf16 v[28:31], v[198:201], v[170:173], v[28:31]
	v_mfma_f32_16x16x32_bf16 v[24:27], v[206:209], v[170:173], v[24:27]
	v_mfma_f32_16x16x32_bf16 v[12:15], v[198:201], v[182:185], v[12:15]
	v_mfma_f32_16x16x32_bf16 v[8:11], v[206:209], v[182:185], v[8:11]
	v_mfma_f32_16x16x32_bf16 v[4:7], v[198:201], v[190:193], v[4:7]
	v_mfma_f32_16x16x32_bf16 v[0:3], v[206:209], v[190:193], v[0:3]
	s_setprio 0
	s_add_i32 s46, 0, 0x18000
	v_add_u32_e32 v154, s46, v139
	s_barrier
	ds_read_b128 v[142:145], v154
	ds_read_b128 v[146:149], v154 offset:1024
	ds_read_b128 v[150:153], v154 offset:2048
	ds_read_b128 v[154:157], v154 offset:3072
	s_add_u32 s16, s16, 0x40000
	s_addc_u32 s17, s17, 0
	s_mov_b32 m0, s23
	ds_read_b128 v[158:161], v141 offset:32768
	ds_read_b128 v[162:165], v141 offset:33792
	ds_read_b128 v[166:169], v141 offset:34816
	ds_read_b128 v[170:173], v141 offset:35840
	ds_read_b128 v[178:181], v141 offset:36864
	ds_read_b128 v[182:185], v141 offset:37888
	ds_read_b128 v[186:189], v141 offset:38912
	ds_read_b128 v[190:193], v141 offset:39936
	global_load_lds_dwordx4 v132, s[16:17]
	s_mov_b32 m0, s26
	s_nop 0
	global_load_lds_dwordx4 v130, s[16:17]
	s_waitcnt lgkmcnt(8)
	s_barrier
	s_waitcnt lgkmcnt(0)
	s_setprio 1
	v_mfma_f32_16x16x32_bf16 v[124:127], v[142:145], v[158:161], v[124:127]
	v_mfma_f32_16x16x32_bf16 v[120:123], v[150:153], v[158:161], v[120:123]
	v_mfma_f32_16x16x32_bf16 v[116:119], v[142:145], v[166:169], v[116:119]
	v_mfma_f32_16x16x32_bf16 v[112:115], v[150:153], v[166:169], v[112:115]
	v_mfma_f32_16x16x32_bf16 v[100:103], v[142:145], v[178:181], v[100:103]
	v_mfma_f32_16x16x32_bf16 v[96:99], v[150:153], v[178:181], v[96:99]
	v_mfma_f32_16x16x32_bf16 v[84:87], v[142:145], v[186:189], v[84:87]
	v_mfma_f32_16x16x32_bf16 v[80:83], v[150:153], v[186:189], v[80:83]
	v_mfma_f32_16x16x32_bf16 v[124:127], v[146:149], v[162:165], v[124:127]
	v_mfma_f32_16x16x32_bf16 v[120:123], v[154:157], v[162:165], v[120:123]
	v_mfma_f32_16x16x32_bf16 v[116:119], v[146:149], v[170:173], v[116:119]
	v_mfma_f32_16x16x32_bf16 v[112:115], v[154:157], v[170:173], v[112:115]
	v_mfma_f32_16x16x32_bf16 v[100:103], v[146:149], v[182:185], v[100:103]
	v_mfma_f32_16x16x32_bf16 v[96:99], v[154:157], v[182:185], v[96:99]
	v_mfma_f32_16x16x32_bf16 v[84:87], v[146:149], v[190:193], v[84:87]
	v_mfma_f32_16x16x32_bf16 v[80:83], v[154:157], v[190:193], v[80:83]
	s_setprio 0
	s_barrier
	s_add_i32 s16, 0, 0x1c000
	s_add_i32 s17, s46, s20
	v_add_u32_e32 v206, s16, v139
	s_mov_b32 m0, s17
	ds_read_b128 v[194:197], v206
	ds_read_b128 v[198:201], v206 offset:1024
	ds_read_b128 v[202:205], v206 offset:2048
	ds_read_b128 v[206:209], v206 offset:3072
	global_load_lds_dwordx4 v176, s[98:99]
	s_add_i32 m0, s17, 0x2000
	s_nop 0
	global_load_lds_dwordx4 v128, s[98:99]
	s_barrier
	s_waitcnt lgkmcnt(0)
	s_setprio 1
	v_mfma_f32_16x16x32_bf16 v[108:111], v[194:197], v[158:161], v[108:111]
	v_mfma_f32_16x16x32_bf16 v[104:107], v[202:205], v[158:161], v[104:107]
	v_mfma_f32_16x16x32_bf16 v[92:95], v[194:197], v[166:169], v[92:95]
	v_mfma_f32_16x16x32_bf16 v[88:91], v[202:205], v[166:169], v[88:91]
	v_mfma_f32_16x16x32_bf16 v[76:79], v[194:197], v[178:181], v[76:79]
	v_mfma_f32_16x16x32_bf16 v[72:75], v[202:205], v[178:181], v[72:75]
	v_mfma_f32_16x16x32_bf16 v[68:71], v[194:197], v[186:189], v[68:71]
	v_mfma_f32_16x16x32_bf16 v[64:67], v[202:205], v[186:189], v[64:67]
	v_mfma_f32_16x16x32_bf16 v[108:111], v[198:201], v[162:165], v[108:111]
	v_mfma_f32_16x16x32_bf16 v[104:107], v[206:209], v[162:165], v[104:107]
	v_mfma_f32_16x16x32_bf16 v[92:95], v[198:201], v[170:173], v[92:95]
	v_mfma_f32_16x16x32_bf16 v[88:91], v[206:209], v[170:173], v[88:91]
	v_mfma_f32_16x16x32_bf16 v[76:79], v[198:201], v[182:185], v[76:79]
	v_mfma_f32_16x16x32_bf16 v[72:75], v[206:209], v[182:185], v[72:75]
	v_mfma_f32_16x16x32_bf16 v[68:71], v[198:201], v[190:193], v[68:71]
	v_mfma_f32_16x16x32_bf16 v[64:67], v[206:209], v[190:193], v[64:67]
	s_setprio 0
	s_mov_b32 m0, s28
	s_barrier
	ds_read_b128 v[158:161], v141 offset:49152
	ds_read_b128 v[162:165], v141 offset:50176
	ds_read_b128 v[166:169], v141 offset:51200
	ds_read_b128 v[170:173], v141 offset:52224
	ds_read_b128 v[178:181], v141 offset:53248
	ds_read_b128 v[182:185], v141 offset:54272
	ds_read_b128 v[186:189], v141 offset:55296
	ds_read_b128 v[190:193], v141 offset:56320
	global_load_lds_dwordx4 v132, s[100:101]
	s_mov_b32 m0, s29
	s_nop 0
	global_load_lds_dwordx4 v130, s[100:101]
	s_barrier
; #define PG8_STAGE(bufoff, gbase, voff) do { _Pragma("unroll") for (int _i = 0; _i < 2; ++_i) \
;         __builtin_amdgcn_global_load_lds((const unsigned*)((const char*)(gbase) + (voff)[_i]), (PG8_LAS unsigned*)(lds + (bufoff) + ldsw + _i * 8192), 16, 0, 0); } while (0)
; #define PG8_MMA(ai, bj, At, Bt) do { __builtin_amdgcn_s_setprio(1); _Pragma("unroll") for (int m = 0; m < 4; ++m) _Pragma("unroll") for (int n = 0; n < 2; ++n) _Pragma("unroll") for (int k = 0; k < 2; ++k) \
;         acc[ai][bj][m][n] = __builtin_amdgcn_mfma_f32_16x16x32_bf16(Bt[n][k], At[m][k], acc[ai][bj][m][n], 0, 0, 0); __builtin_amdgcn_s_setprio(0); } while (0)
; #define PG8_WAIT_V(n) asm volatile("s_waitcnt vmcnt(" #n ")" ::: "memory")
; #define PG8_WAIT_L(n) asm volatile("s_waitcnt lgkmcnt(" #n ")" ::: "memory")
; #define PG8_BAR __builtin_amdgcn_s_barrier()
; #define PG8_SCHED __builtin_amdgcn_sched_barrier(0)
; template <class Epi, class Sched>
; __device__ __forceinline__ void gemm_phase(PG8_LAS unsigned char* lds, const Gemm g, const Sched& S, const Epi& E) {
;     ...
;             PG8_BAR; PG8_WAIT_L(0); PG8_MMA(1, 0, At, B0); PG8_BAR; PG8_SCHED;
;             PG8_STAGE(PG8_SB(1, 1), b3 + hstep, voffB);
;             PG8_WAIT_V(6); PG8_BAR; PG8_MMA(1, 1, At, B1); PG8_BAR;
;         }
	s_waitcnt lgkmcnt(0)
	s_setprio 1
	v_mfma_f32_16x16x32_bf16 v[60:63], v[142:145], v[158:161], v[60:63]
	v_mfma_f32_16x16x32_bf16 v[56:59], v[150:153], v[158:161], v[56:59]
	v_mfma_f32_16x16x32_bf16 v[52:55], v[142:145], v[166:169], v[52:55]
	v_mfma_f32_16x16x32_bf16 v[48:51], v[150:153], v[166:169], v[48:51]
	v_mfma_f32_16x16x32_bf16 v[36:39], v[142:145], v[178:181], v[36:39]
	v_mfma_f32_16x16x32_bf16 v[32:35], v[150:153], v[178:181], v[32:35]
	v_mfma_f32_16x16x32_bf16 v[20:23], v[142:145], v[186:189], v[20:23]
	v_mfma_f32_16x16x32_bf16 v[16:19], v[150:153], v[186:189], v[16:19]
	v_mfma_f32_16x16x32_bf16 v[60:63], v[146:149], v[162:165], v[60:63]
	v_mfma_f32_16x16x32_bf16 v[56:59], v[154:157], v[162:165], v[56:59]
	v_mfma_f32_16x16x32_bf16 v[52:55], v[146:149], v[170:173], v[52:55]
	v_mfma_f32_16x16x32_bf16 v[48:51], v[154:157], v[170:173], v[48:51]
	v_mfma_f32_16x16x32_bf16 v[36:39], v[146:149], v[182:185], v[36:39]
	v_mfma_f32_16x16x32_bf16 v[32:35], v[154:157], v[182:185], v[32:35]
	v_mfma_f32_16x16x32_bf16 v[20:23], v[146:149], v[190:193], v[20:23]
	v_mfma_f32_16x16x32_bf16 v[16:19], v[154:157], v[190:193], v[16:19]
	s_setprio 0
	s_barrier
	s_add_u32 s14, s14, 0x40080
	s_addc_u32 s15, s15, 0
	s_add_i32 s16, s16, s20
	s_mov_b32 m0, s16
	s_nop 0
	global_load_lds_dwordx4 v176, s[14:15]
	s_add_i32 m0, s16, 0x2000
	s_nop 0
	global_load_lds_dwordx4 v128, s[14:15]
	s_waitcnt vmcnt(6)
	s_barrier
	s_setprio 1
	v_mfma_f32_16x16x32_bf16 v[44:47], v[194:197], v[158:161], v[44:47]
	v_mfma_f32_16x16x32_bf16 v[40:43], v[202:205], v[158:161], v[40:43]
	v_mfma_f32_16x16x32_bf16 v[28:31], v[194:197], v[166:169], v[28:31]
	v_mfma_f32_16x16x32_bf16 v[24:27], v[202:205], v[166:169], v[24:27]
	v_mfma_f32_16x16x32_bf16 v[12:15], v[194:197], v[178:181], v[12:15]
	v_mfma_f32_16x16x32_bf16 v[8:11], v[202:205], v[178:181], v[8:11]
	v_mfma_f32_16x16x32_bf16 v[4:7], v[194:197], v[186:189], v[4:7]
	v_mfma_f32_16x16x32_bf16 v[0:3], v[202:205], v[186:189], v[0:3]
	v_mfma_f32_16x16x32_bf16 v[44:47], v[198:201], v[162:165], v[44:47]
	v_mfma_f32_16x16x32_bf16 v[40:43], v[206:209], v[162:165], v[40:43]
	v_mfma_f32_16x16x32_bf16 v[28:31], v[198:201], v[170:173], v[28:31]
	v_mfma_f32_16x16x32_bf16 v[24:27], v[206:209], v[170:173], v[24:27]
	v_mfma_f32_16x16x32_bf16 v[12:15], v[198:201], v[182:185], v[12:15]
	v_mfma_f32_16x16x32_bf16 v[8:11], v[206:209], v[182:185], v[8:11]
	v_mfma_f32_16x16x32_bf16 v[4:7], v[198:201], v[190:193], v[4:7]
	v_mfma_f32_16x16x32_bf16 v[0:3], v[206:209], v[190:193], v[0:3]
	s_setprio 0
	s_add_i32 s45, s45, 2
	s_add_u32 s12, s12, 0x100
	s_addc_u32 s13, s13, 0
	s_add_u32 s43, s43, 0x100
	s_addc_u32 s44, s44, 0
	s_cmp_gt_u32 s45, 13
	s_barrier
	s_cbranch_scc0 .LBB0_137
; __device__ __forceinline__ unsigned cvtpk(float lo, float hi) { const f32x2 v = (f32x2){lo, hi}; const bf16v2 b = __builtin_convertvector(v, bf16v2); return __builtin_bit_cast(unsigned, b); }
; #define PG8_WAIT_V(n) asm volatile("s_waitcnt vmcnt(" #n ")" ::: "memory")
; #define PG8_BAR __builtin_amdgcn_s_barrier()
; template <class Epi, class Sched>
; __device__ __forceinline__ void gemm_phase(PG8_LAS unsigned char* lds, const Gemm g, const Sched& S, const Epi& E) {
;     ...
;         if constexpr (!Epi::AFTER_DRAIN) { E(acc, cur, wr, wc, fr, fq); S.done(cur); }
;         if (!has_next) break;
; #pragma unroll
;         for (int a = 0; a < 2; ++a)
; #pragma unroll
;             for (int b = 0; b < 2; ++b)
; #pragma unroll
;                 for (int m = 0; m < 4; ++m)
; #pragma unroll
;                     for (int n = 0; n < 2; ++n) acc[a][b][m][n] = (f32x4){0.f, 0.f, 0.f, 0.f};
;         cur = nxt; cA = nA; cB = nB; ++ui;
;     }
;     PG8_WAIT_V(0);
;     if (wr == 0) PG8_BAR;
;     __device__ __forceinline__ void operator()(const f32x4 (&acc)[2][2][4][2], const pg8::Unit& u, int wr, int wc, int fr, int fq) const {
;         const int row0 = u.pm * 256 + wr * 64 + fr, col0 = u.pn * 256 + wc * 32 + 8 * fq;
; #pragma unroll
;         for (int ai = 0; ai < 2; ++ai)
; #pragma unroll
;             for (int m = 0; m < 4; ++m) { bf16_t* rowp = O + (size_t)(row0 + ai * 128 + m * 16) * ldc + col0;
; #pragma unroll
;                 for (int bj = 0; bj < 2; ++bj) { const f32x4 v0 = acc[ai][bj][m][0], v1 = acc[ai][bj][m][1];
;                     u32x4 w; w.x = cvtpk(v0[0], v0[1]); w.y = cvtpk(v0[2], v0[3]); w.z = cvtpk(v1[0], v1[1]); w.w = cvtpk(v1[2], v1[3]);
;                     *(u32x4*)(rowp + bj * 128) = w; } }
	v_lshl_add_u32 v142, s0, 8, v138
	v_lshl_or_b32 v144, s34, 8, v140
	v_ashrrev_i32_e32 v143, 31, v142
	v_readlane_b32 s12, v253, 18
	v_ashrrev_i32_e32 v145, 31, v144
	v_lshlrev_b64 v[146:147], 11, v[142:143]
	v_readlane_b32 s13, v253, 19
	v_cvt_pk_bf16_f32 v108, v108, v109
	v_cvt_pk_bf16_f32 v109, v110, v111
	v_cvt_pk_bf16_f32 v110, v104, v105
	v_or_b32_e32 v104, 16, v142
	v_cvt_pk_bf16_f32 v92, v92, v93
	v_cvt_pk_bf16_f32 v93, v94, v95
	v_cvt_pk_bf16_f32 v94, v88, v89
	v_or_b32_e32 v88, 32, v142
	v_cvt_pk_bf16_f32 v76, v76, v77
	v_cvt_pk_bf16_f32 v77, v78, v79
	v_cvt_pk_bf16_f32 v78, v72, v73
	v_or_b32_e32 v72, 48, v142
	v_lshl_add_u64 v[146:147], s[12:13], 0, v[146:147]
	v_lshlrev_b64 v[144:145], 1, v[144:145]
	v_ashrrev_i32_e32 v105, 31, v104
	v_ashrrev_i32_e32 v89, 31, v88
	v_ashrrev_i32_e32 v73, 31, v72
	v_lshl_add_u64 v[146:147], v[146:147], 0, v[144:145]
	v_lshlrev_b64 v[104:105], 11, v[104:105]
	v_lshlrev_b64 v[88:89], 11, v[88:89]
	v_lshlrev_b64 v[72:73], 11, v[72:73]
	v_lshl_add_u64 v[104:105], s[12:13], 0, v[104:105]
	v_lshl_add_u64 v[88:89], s[12:13], 0, v[88:89]
	v_lshl_add_u64 v[72:73], s[12:13], 0, v[72:73]
	s_mov_b64 s[12:13], 0x40000
	v_cvt_pk_bf16_f32 v60, v60, v61
	v_cvt_pk_bf16_f32 v61, v62, v63
	v_cvt_pk_bf16_f32 v62, v56, v57
	v_add_co_u32_e32 v56, vcc, s2, v146
	v_cvt_pk_bf16_f32 v68, v68, v69
	v_cvt_pk_bf16_f32 v69, v70, v71
	v_cvt_pk_bf16_f32 v70, v64, v65
	v_lshl_add_u64 v[64:65], v[146:147], 0, s[12:13]
	v_addc_co_u32_e32 v57, vcc, 0, v147, vcc
	v_cvt_pk_bf16_f32 v44, v44, v45
	v_cvt_pk_bf16_f32 v45, v46, v47
	v_cvt_pk_bf16_f32 v46, v40, v41
	v_cvt_pk_bf16_f32 v47, v42, v43
	s_mov_b32 s0, 0x48000
	global_store_dwordx4 v[64:65], v[44:47], off offset:256
	s_mov_b64 s[12:13], 0x48000
	v_cvt_pk_bf16_f32 v28, v28, v29
	v_add_co_u32_e32 v46, vcc, s0, v146
	v_lshl_add_u64 v[44:45], v[146:147], 0, s[12:13]
	s_nop 0
	v_addc_co_u32_e32 v47, vcc, 0, v147, vcc
	v_cvt_pk_bf16_f32 v29, v30, v31
	v_cvt_pk_bf16_f32 v30, v24, v25
	v_cvt_pk_bf16_f32 v31, v26, v27
	s_mov_b32 s0, 0x50000
	global_store_dwordx4 v[44:45], v[28:31], off offset:256
	s_mov_b64 s[12:13], 0x50000
	v_cvt_pk_bf16_f32 v111, v106, v107
	v_add_co_u32_e32 v30, vcc, s0, v146
	v_lshl_add_u64 v[28:29], v[146:147], 0, s[12:13]
	s_nop 0
	v_addc_co_u32_e32 v31, vcc, 0, v147, vcc
	v_cvt_pk_bf16_f32 v12, v12, v13
	v_cvt_pk_bf16_f32 v13, v14, v15
	v_cvt_pk_bf16_f32 v14, v8, v9
	v_cvt_pk_bf16_f32 v15, v10, v11
	s_mov_b32 s0, 0x58000
	global_store_dwordx4 v[146:147], v[108:111], off offset:256
	v_cvt_pk_bf16_f32 v95, v90, v91
	global_store_dwordx4 v[28:29], v[12:15], off offset:256
	v_lshl_add_u64 v[108:109], v[104:105], 0, v[144:145]
	global_store_dwordx4 v[108:109], v[92:95], off offset:256
	v_add_co_u32_e32 v14, vcc, s0, v146
	s_nop 0
	v_lshl_add_u64 v[92:93], v[88:89], 0, v[144:145]
	v_cvt_pk_bf16_f32 v79, v74, v75
	s_mov_b64 s[12:13], 0x58000
	v_addc_co_u32_e32 v15, vcc, 0, v147, vcc
	v_cvt_pk_bf16_f32 v124, v124, v125
	v_cvt_pk_bf16_f32 v125, v126, v127
	v_cvt_pk_bf16_f32 v126, v120, v121
	v_cvt_pk_bf16_f32 v127, v122, v123
	v_cvt_pk_bf16_f32 v104, v116, v117
	v_cvt_pk_bf16_f32 v105, v118, v119
	v_cvt_pk_bf16_f32 v106, v112, v113
	v_cvt_pk_bf16_f32 v107, v114, v115
	v_cvt_pk_bf16_f32 v88, v100, v101
	v_cvt_pk_bf16_f32 v89, v102, v103
	v_cvt_pk_bf16_f32 v90, v96, v97
	v_cvt_pk_bf16_f32 v91, v98, v99
	global_store_dwordx4 v[92:93], v[76:79], off offset:256
	v_cvt_pk_bf16_f32 v74, v80, v81
	v_cvt_pk_bf16_f32 v75, v82, v83
	v_lshl_add_u64 v[76:77], v[72:73], 0, v[144:145]
	v_cvt_pk_bf16_f32 v72, v84, v85
	v_cvt_pk_bf16_f32 v73, v86, v87
	v_cvt_pk_bf16_f32 v71, v66, v67
	v_cvt_pk_bf16_f32 v63, v58, v59
	v_cvt_pk_bf16_f32 v40, v52, v53
	v_cvt_pk_bf16_f32 v41, v54, v55
	v_cvt_pk_bf16_f32 v42, v48, v49
	v_cvt_pk_bf16_f32 v43, v50, v51
	v_cvt_pk_bf16_f32 v24, v36, v37
	v_cvt_pk_bf16_f32 v25, v38, v39
	v_cvt_pk_bf16_f32 v26, v32, v33
	v_cvt_pk_bf16_f32 v27, v34, v35
	v_lshl_add_u64 v[12:13], v[146:147], 0, s[12:13]
	v_cvt_pk_bf16_f32 v8, v20, v21
	v_cvt_pk_bf16_f32 v9, v22, v23
	v_cvt_pk_bf16_f32 v10, v16, v17
	v_cvt_pk_bf16_f32 v11, v18, v19
	v_cvt_pk_bf16_f32 v4, v4, v5
	v_cvt_pk_bf16_f32 v5, v6, v7
	v_cvt_pk_bf16_f32 v6, v0, v1
	v_cvt_pk_bf16_f32 v7, v2, v3
	s_and_b64 vcc, exec, s[38:39]
	s_mov_b32 s34, s4
	s_mov_b32 s0, s6
	s_mov_b64 s[14:15], s[10:11]
	s_mov_b64 s[12:13], s[8:9]
	global_store_dwordx4 v[146:147], v[124:127], off
	global_store_dwordx4 v[108:109], v[104:107], off
	global_store_dwordx4 v[92:93], v[88:91], off
	global_store_dwordx4 v[76:77], v[72:75], off
	global_store_dwordx4 v[76:77], v[68:71], off offset:256
	global_store_dwordx4 v[56:57], v[60:63], off
	global_store_dwordx4 v[46:47], v[40:43], off
	global_store_dwordx4 v[30:31], v[24:27], off
	global_store_dwordx4 v[14:15], v[8:11], off
	global_store_dwordx4 v[12:13], v[4:7], off offset:256
	s_cbranch_vccz .LBB0_134
	s_waitcnt vmcnt(0)
	v_readlane_b32 s22, v255, 14
	s_cmpk_gt_u32 s19, 0xff
	v_readlane_b32 s23, v255, 15
	s_mov_b64 s[28:29], s[54:55]
	s_cbranch_scc1 .LBB0_141
	s_barrier

; #define PG8_STAGE(bufoff, gbase, voff) do { _Pragma("unroll") for (int _i = 0; _i < 2; ++_i) \
;         __builtin_amdgcn_global_load_lds((const unsigned*)((const char*)(gbase) + (voff)[_i]), (PG8_LAS unsigned*)(lds + (bufoff) + ldsw + _i * 8192), 16, 0, 0); } while (0)
; #define PG8_LDA(dst, b, h) do { _Pragma("unroll") for (int m = 0; m < 4; ++m) _Pragma("unroll") for (int k = 0; k < 2; ++k) dst[m][k] = *(const PG8_LAS bf16x8*)(lds + PG8_SA(b, h) + aoff + m * 2048 + k * 1024); } while (0)
; #define PG8_LDB(dst, b, h) do { _Pragma("unroll") for (int n = 0; n < 2; ++n) _Pragma("unroll") for (int k = 0; k < 2; ++k) dst[n][k] = *(const PG8_LAS bf16x8*)(lds + PG8_SB(b, h) + boff + n * 2048 + k * 1024); } while (0)
; #define PG8_MMA(ai, bj, At, Bt) do { __builtin_amdgcn_s_setprio(1); _Pragma("unroll") for (int m = 0; m < 4; ++m) _Pragma("unroll") for (int n = 0; n < 2; ++n) _Pragma("unroll") for (int k = 0; k < 2; ++k) \
;         acc[ai][bj][m][n] = __builtin_amdgcn_mfma_f32_16x16x32_bf16(Bt[n][k], At[m][k], acc[ai][bj][m][n], 0, 0, 0); __builtin_amdgcn_s_setprio(0); } while (0)
; #define PG8_WAIT_V(n) asm volatile("s_waitcnt vmcnt(" #n ")" ::: "memory")
; template <class Epi, class Sched>
; __device__ __forceinline__ void gemm_phase(PG8_LAS unsigned char* lds, const Gemm g, const Sched& S, const Epi& E) {
;     ...
;         for (int t = 0; t < nt; t += 2) {
;             const bool last = (t == nt - 2);
;             const char* a1 = cA + (size_t)(t + 1) * kstep;
;             const char* a2 = last ? nA : cA + (size_t)(t + 2) * kstep; const char* b2 = last ? nB : cB + (size_t)(t + 2) * kstep;
;             const char* a3 = a2 + kstep; const char* b3 = b2 + kstep;
;             if (last && has_next) S.a_ready(nxt);
;             PG8_LDB(B0, 0, 0); PG8_SCHED; PG8_LDA(At, 0, 0); PG8_STAGE(PG8_SA(1, 1), a1 + hstep, voffA);
;             PG8_WAIT_L(8); PG8_BAR; PG8_WAIT_L(0); PG8_MMA(0, 0, At, B0); PG8_BAR; PG8_SCHED;
;             PG8_LDB(B1, 0, 1); PG8_STAGE(PG8_SB(0, 0), b2, voffB);
;             PG8_BAR; PG8_WAIT_L(0); PG8_MMA(0, 1, At, B1); PG8_BAR;
;             PG8_LDA(At, 0, 1); PG8_STAGE(PG8_SA(0, 0), a2, voffA);
;             PG8_BAR; PG8_WAIT_L(0); PG8_MMA(1, 0, At, B0); PG8_BAR; PG8_SCHED;
;             PG8_STAGE(PG8_SB(0, 1), b2 + hstep, voffB);
;             PG8_WAIT_V(6); PG8_BAR; PG8_MMA(1, 1, At, B1); PG8_BAR;
.LBB0_358:
	s_add_u32 s14, s12, 0xfffc0080
	s_addc_u32 s15, s13, -1
	s_add_i32 s46, 0, 0x10000
	v_add_u32_e32 v154, s46, v139
	ds_read_b128 v[142:145], v154
	ds_read_b128 v[146:149], v154 offset:1024
	ds_read_b128 v[150:153], v154 offset:2048
	ds_read_b128 v[154:157], v154 offset:3072
	s_cmp_eq_u32 s45, 12
	s_cselect_b32 s17, s7, s15
	s_cselect_b32 s16, s40, s14
	s_cselect_b32 s15, s5, s44
	s_cselect_b32 s14, s41, s43
	s_add_i32 m0, s1, 0xc000
	ds_read_b128 v[158:161], v141
	ds_read_b128 v[162:165], v141 offset:1024
	ds_read_b128 v[166:169], v141 offset:2048
	ds_read_b128 v[170:173], v141 offset:3072
	ds_read_b128 v[182:185], v141 offset:4096
	ds_read_b128 v[190:193], v141 offset:5120
	ds_read_b128 v[194:197], v141 offset:6144
	ds_read_b128 v[198:201], v141 offset:7168
	global_load_lds_dwordx4 v134, s[12:13]
	s_add_i32 m0, s1, 0xe000
	s_nop 0
	global_load_lds_dwordx4 v136, s[12:13]
	s_waitcnt lgkmcnt(8)
	s_barrier
	s_waitcnt lgkmcnt(0)
	s_setprio 1
	v_mfma_f32_16x16x32_bf16 v[124:127], v[142:145], v[158:161], v[124:127]
	v_mfma_f32_16x16x32_bf16 v[120:123], v[150:153], v[158:161], v[120:123]
	v_mfma_f32_16x16x32_bf16 v[116:119], v[142:145], v[166:169], v[116:119]
	v_mfma_f32_16x16x32_bf16 v[112:115], v[150:153], v[166:169], v[112:115]
	v_mfma_f32_16x16x32_bf16 v[100:103], v[142:145], v[182:185], v[100:103]
	v_mfma_f32_16x16x32_bf16 v[96:99], v[150:153], v[182:185], v[96:99]
	v_mfma_f32_16x16x32_bf16 v[84:87], v[142:145], v[194:197], v[84:87]
	v_mfma_f32_16x16x32_bf16 v[80:83], v[150:153], v[194:197], v[80:83]
	v_mfma_f32_16x16x32_bf16 v[124:127], v[146:149], v[162:165], v[124:127]
	v_mfma_f32_16x16x32_bf16 v[120:123], v[154:157], v[162:165], v[120:123]
	v_mfma_f32_16x16x32_bf16 v[116:119], v[146:149], v[170:173], v[116:119]
	v_mfma_f32_16x16x32_bf16 v[112:115], v[154:157], v[170:173], v[112:115]
	v_mfma_f32_16x16x32_bf16 v[100:103], v[146:149], v[190:193], v[100:103]
	v_mfma_f32_16x16x32_bf16 v[96:99], v[154:157], v[190:193], v[96:99]
	v_mfma_f32_16x16x32_bf16 v[84:87], v[146:149], v[198:201], v[84:87]
	v_mfma_f32_16x16x32_bf16 v[80:83], v[154:157], v[198:201], v[80:83]
	s_setprio 0
	s_barrier
	s_add_i32 s48, 0, 0x14000
	v_add_u32_e32 v174, s48, v139
	s_add_i32 s46, s46, s20
	ds_read_b128 v[202:205], v174
	ds_read_b128 v[206:209], v174 offset:1024
	ds_read_b128 v[210:213], v174 offset:2048
	ds_read_b128 v[214:217], v174 offset:3072
	s_add_u32 s98, s14, 0x80
	s_addc_u32 s99, s15, 0
	s_mov_b32 m0, s46
	s_nop 0
	global_load_lds_dwordx4 v176, s[14:15]
	s_add_i32 m0, s46, 0x2000
	s_nop 0
	global_load_lds_dwordx4 v128, s[14:15]
	s_barrier
	s_waitcnt lgkmcnt(0)
	s_setprio 1
	v_mfma_f32_16x16x32_bf16 v[108:111], v[202:205], v[158:161], v[108:111]
	v_mfma_f32_16x16x32_bf16 v[104:107], v[210:213], v[158:161], v[104:107]
	v_mfma_f32_16x16x32_bf16 v[92:95], v[202:205], v[166:169], v[92:95]
	v_mfma_f32_16x16x32_bf16 v[88:91], v[210:213], v[166:169], v[88:91]
	v_mfma_f32_16x16x32_bf16 v[76:79], v[202:205], v[182:185], v[76:79]
	v_mfma_f32_16x16x32_bf16 v[72:75], v[210:213], v[182:185], v[72:75]
	v_mfma_f32_16x16x32_bf16 v[68:71], v[202:205], v[194:197], v[68:71]
	v_mfma_f32_16x16x32_bf16 v[64:67], v[210:213], v[194:197], v[64:67]
	v_mfma_f32_16x16x32_bf16 v[108:111], v[206:209], v[162:165], v[108:111]
	v_mfma_f32_16x16x32_bf16 v[104:107], v[214:217], v[162:165], v[104:107]
	v_mfma_f32_16x16x32_bf16 v[92:95], v[206:209], v[170:173], v[92:95]
	v_mfma_f32_16x16x32_bf16 v[88:91], v[214:217], v[170:173], v[88:91]
	v_mfma_f32_16x16x32_bf16 v[76:79], v[206:209], v[190:193], v[76:79]
	v_mfma_f32_16x16x32_bf16 v[72:75], v[214:217], v[190:193], v[72:75]
	v_mfma_f32_16x16x32_bf16 v[68:71], v[206:209], v[198:201], v[68:71]
	v_mfma_f32_16x16x32_bf16 v[64:67], v[214:217], v[198:201], v[64:67]
	s_setprio 0
	s_mov_b32 m0, s1
	s_add_u32 s100, s16, 0x80
	s_addc_u32 s101, s17, 0
	s_barrier
	ds_read_b128 v[158:161], v141 offset:16384
	ds_read_b128 v[162:165], v141 offset:17408
	ds_read_b128 v[166:169], v141 offset:18432
	ds_read_b128 v[170:173], v141 offset:19456
	ds_read_b128 v[182:185], v141 offset:20480
	ds_read_b128 v[190:193], v141 offset:21504
	ds_read_b128 v[194:197], v141 offset:22528
	ds_read_b128 v[198:201], v141 offset:23552
	global_load_lds_dwordx4 v132, s[16:17]
	s_mov_b32 m0, s22
	s_nop 0
	global_load_lds_dwordx4 v130, s[16:17]
	s_barrier
	s_waitcnt lgkmcnt(0)
	s_setprio 1
	v_mfma_f32_16x16x32_bf16 v[60:63], v[142:145], v[158:161], v[60:63]
	v_mfma_f32_16x16x32_bf16 v[56:59], v[150:153], v[158:161], v[56:59]
	v_mfma_f32_16x16x32_bf16 v[52:55], v[142:145], v[166:169], v[52:55]
	v_mfma_f32_16x16x32_bf16 v[48:51], v[150:153], v[166:169], v[48:51]
	v_mfma_f32_16x16x32_bf16 v[36:39], v[142:145], v[182:185], v[36:39]
	v_mfma_f32_16x16x32_bf16 v[32:35], v[150:153], v[182:185], v[32:35]
	v_mfma_f32_16x16x32_bf16 v[20:23], v[142:145], v[194:197], v[20:23]
	v_mfma_f32_16x16x32_bf16 v[16:19], v[150:153], v[194:197], v[16:19]
	v_mfma_f32_16x16x32_bf16 v[60:63], v[146:149], v[162:165], v[60:63]
	v_mfma_f32_16x16x32_bf16 v[56:59], v[154:157], v[162:165], v[56:59]
	v_mfma_f32_16x16x32_bf16 v[52:55], v[146:149], v[170:173], v[52:55]
	v_mfma_f32_16x16x32_bf16 v[48:51], v[154:157], v[170:173], v[48:51]
	v_mfma_f32_16x16x32_bf16 v[36:39], v[146:149], v[190:193], v[36:39]
	v_mfma_f32_16x16x32_bf16 v[32:35], v[154:157], v[190:193], v[32:35]
	v_mfma_f32_16x16x32_bf16 v[20:23], v[146:149], v[198:201], v[20:23]
	v_mfma_f32_16x16x32_bf16 v[16:19], v[154:157], v[198:201], v[16:19]
	s_setprio 0
	s_barrier
	s_add_u32 s46, s14, 0x40000
	s_addc_u32 s47, s15, 0
	s_add_i32 s48, s48, s20
	s_mov_b32 m0, s48
	s_nop 0
	global_load_lds_dwordx4 v176, s[46:47]
	s_add_i32 m0, s48, 0x2000
	s_nop 0
	global_load_lds_dwordx4 v128, s[46:47]
	s_waitcnt vmcnt(6)
	s_barrier
; #define PG8_STAGE(bufoff, gbase, voff) do { _Pragma("unroll") for (int _i = 0; _i < 2; ++_i) \
;         __builtin_amdgcn_global_load_lds((const unsigned*)((const char*)(gbase) + (voff)[_i]), (PG8_LAS unsigned*)(lds + (bufoff) + ldsw + _i * 8192), 16, 0, 0); } while (0)
; #define PG8_LDA(dst, b, h) do { _Pragma("unroll") for (int m = 0; m < 4; ++m) _Pragma("unroll") for (int k = 0; k < 2; ++k) dst[m][k] = *(const PG8_LAS bf16x8*)(lds + PG8_SA(b, h) + aoff + m * 2048 + k * 1024); } while (0)
; #define PG8_LDB(dst, b, h) do { _Pragma("unroll") for (int n = 0; n < 2; ++n) _Pragma("unroll") for (int k = 0; k < 2; ++k) dst[n][k] = *(const PG8_LAS bf16x8*)(lds + PG8_SB(b, h) + boff + n * 2048 + k * 1024); } while (0)
; #define PG8_MMA(ai, bj, At, Bt) do { __builtin_amdgcn_s_setprio(1); _Pragma("unroll") for (int m = 0; m < 4; ++m) _Pragma("unroll") for (int n = 0; n < 2; ++n) _Pragma("unroll") for (int k = 0; k < 2; ++k) \
;         acc[ai][bj][m][n] = __builtin_amdgcn_mfma_f32_16x16x32_bf16(Bt[n][k], At[m][k], acc[ai][bj][m][n], 0, 0, 0); __builtin_amdgcn_s_setprio(0); } while (0)
; #define PG8_WAIT_V(n) asm volatile("s_waitcnt vmcnt(" #n ")" ::: "memory")
; #define PG8_WAIT_L(n) asm volatile("s_waitcnt lgkmcnt(" #n ")" ::: "memory")
; #define PG8_BAR __builtin_amdgcn_s_barrier()
; #define PG8_SCHED __builtin_amdgcn_sched_barrier(0)
; template <class Epi, class Sched>
; __device__ __forceinline__ void gemm_phase(PG8_LAS unsigned char* lds, const Gemm g, const Sched& S, const Epi& E) {
;     ...
;             PG8_WAIT_V(6); PG8_BAR; PG8_MMA(1, 1, At, B1); PG8_BAR;
;             PG8_LDB(B0, 1, 0); PG8_SCHED; PG8_LDA(At, 1, 0); PG8_STAGE(PG8_SA(0, 1), a2 + hstep, voffA);
;             PG8_WAIT_L(8); PG8_BAR; PG8_WAIT_L(0); PG8_MMA(0, 0, At, B0); PG8_BAR; PG8_SCHED;
;             PG8_LDB(B1, 1, 1); PG8_STAGE(PG8_SB(1, 0), b3, voffB);
;             PG8_BAR; PG8_WAIT_L(0); PG8_MMA(0, 1, At, B1); PG8_BAR;
;             PG8_LDA(At, 1, 1); PG8_STAGE(PG8_SA(1, 0), a3, voffA);
;             PG8_BAR; PG8_WAIT_L(0); PG8_MMA(1, 0, At, B0); PG8_BAR; PG8_SCHED;
	s_setprio 1
	v_mfma_f32_16x16x32_bf16 v[44:47], v[202:205], v[158:161], v[44:47]
	v_mfma_f32_16x16x32_bf16 v[40:43], v[210:213], v[158:161], v[40:43]
	v_mfma_f32_16x16x32_bf16 v[28:31], v[202:205], v[166:169], v[28:31]
	v_mfma_f32_16x16x32_bf16 v[24:27], v[210:213], v[166:169], v[24:27]
	v_mfma_f32_16x16x32_bf16 v[12:15], v[202:205], v[182:185], v[12:15]
	v_mfma_f32_16x16x32_bf16 v[8:11], v[210:213], v[182:185], v[8:11]
	v_mfma_f32_16x16x32_bf16 v[4:7], v[202:205], v[194:197], v[4:7]
	v_mfma_f32_16x16x32_bf16 v[0:3], v[210:213], v[194:197], v[0:3]
	v_mfma_f32_16x16x32_bf16 v[44:47], v[206:209], v[162:165], v[44:47]
	v_mfma_f32_16x16x32_bf16 v[40:43], v[214:217], v[162:165], v[40:43]
	v_mfma_f32_16x16x32_bf16 v[28:31], v[206:209], v[170:173], v[28:31]
	v_mfma_f32_16x16x32_bf16 v[24:27], v[214:217], v[170:173], v[24:27]
	v_mfma_f32_16x16x32_bf16 v[12:15], v[206:209], v[190:193], v[12:15]
	v_mfma_f32_16x16x32_bf16 v[8:11], v[214:217], v[190:193], v[8:11]
	v_mfma_f32_16x16x32_bf16 v[4:7], v[206:209], v[198:201], v[4:7]
	v_mfma_f32_16x16x32_bf16 v[0:3], v[214:217], v[198:201], v[0:3]
	s_setprio 0
	s_add_i32 s46, 0, 0x18000
	v_add_u32_e32 v154, s46, v139
	s_barrier
	ds_read_b128 v[142:145], v154
	ds_read_b128 v[146:149], v154 offset:1024
	ds_read_b128 v[150:153], v154 offset:2048
	ds_read_b128 v[154:157], v154 offset:3072
	s_add_u32 s16, s16, 0x40000
	s_addc_u32 s17, s17, 0
	s_mov_b32 m0, s23
	ds_read_b128 v[158:161], v141 offset:32768
	ds_read_b128 v[162:165], v141 offset:33792
	ds_read_b128 v[166:169], v141 offset:34816
	ds_read_b128 v[170:173], v141 offset:35840
	ds_read_b128 v[182:185], v141 offset:36864
	ds_read_b128 v[190:193], v141 offset:37888
	ds_read_b128 v[194:197], v141 offset:38912
	ds_read_b128 v[198:201], v141 offset:39936
	global_load_lds_dwordx4 v132, s[16:17]
	s_mov_b32 m0, s26
	s_nop 0
	global_load_lds_dwordx4 v130, s[16:17]
	s_waitcnt lgkmcnt(8)
	s_barrier
	s_waitcnt lgkmcnt(0)
	s_setprio 1
	v_mfma_f32_16x16x32_bf16 v[124:127], v[142:145], v[158:161], v[124:127]
	v_mfma_f32_16x16x32_bf16 v[120:123], v[150:153], v[158:161], v[120:123]
	v_mfma_f32_16x16x32_bf16 v[116:119], v[142:145], v[166:169], v[116:119]
	v_mfma_f32_16x16x32_bf16 v[112:115], v[150:153], v[166:169], v[112:115]
	v_mfma_f32_16x16x32_bf16 v[100:103], v[142:145], v[182:185], v[100:103]
	v_mfma_f32_16x16x32_bf16 v[96:99], v[150:153], v[182:185], v[96:99]
	v_mfma_f32_16x16x32_bf16 v[84:87], v[142:145], v[194:197], v[84:87]
	v_mfma_f32_16x16x32_bf16 v[80:83], v[150:153], v[194:197], v[80:83]
	v_mfma_f32_16x16x32_bf16 v[124:127], v[146:149], v[162:165], v[124:127]
	v_mfma_f32_16x16x32_bf16 v[120:123], v[154:157], v[162:165], v[120:123]
	v_mfma_f32_16x16x32_bf16 v[116:119], v[146:149], v[170:173], v[116:119]
	v_mfma_f32_16x16x32_bf16 v[112:115], v[154:157], v[170:173], v[112:115]
	v_mfma_f32_16x16x32_bf16 v[100:103], v[146:149], v[190:193], v[100:103]
	v_mfma_f32_16x16x32_bf16 v[96:99], v[154:157], v[190:193], v[96:99]
	v_mfma_f32_16x16x32_bf16 v[84:87], v[146:149], v[198:201], v[84:87]
	v_mfma_f32_16x16x32_bf16 v[80:83], v[154:157], v[198:201], v[80:83]
	s_setprio 0
	s_barrier
	s_add_i32 s16, 0, 0x1c000
	s_add_i32 s17, s46, s20
	v_add_u32_e32 v188, s16, v139
	s_mov_b32 m0, s17
	ds_read_b128 v[202:205], v188
	ds_read_b128 v[206:209], v188 offset:1024
	ds_read_b128 v[210:213], v188 offset:2048
	ds_read_b128 v[214:217], v188 offset:3072
	global_load_lds_dwordx4 v176, s[98:99]
	s_add_i32 m0, s17, 0x2000
	s_nop 0
	global_load_lds_dwordx4 v128, s[98:99]
	s_barrier
	s_waitcnt lgkmcnt(0)
	s_setprio 1
	v_mfma_f32_16x16x32_bf16 v[108:111], v[202:205], v[158:161], v[108:111]
	v_mfma_f32_16x16x32_bf16 v[104:107], v[210:213], v[158:161], v[104:107]
	v_mfma_f32_16x16x32_bf16 v[92:95], v[202:205], v[166:169], v[92:95]
	v_mfma_f32_16x16x32_bf16 v[88:91], v[210:213], v[166:169], v[88:91]
	v_mfma_f32_16x16x32_bf16 v[76:79], v[202:205], v[182:185], v[76:79]
	v_mfma_f32_16x16x32_bf16 v[72:75], v[210:213], v[182:185], v[72:75]
	v_mfma_f32_16x16x32_bf16 v[68:71], v[202:205], v[194:197], v[68:71]
	v_mfma_f32_16x16x32_bf16 v[64:67], v[210:213], v[194:197], v[64:67]
	v_mfma_f32_16x16x32_bf16 v[108:111], v[206:209], v[162:165], v[108:111]
	v_mfma_f32_16x16x32_bf16 v[104:107], v[214:217], v[162:165], v[104:107]
	v_mfma_f32_16x16x32_bf16 v[92:95], v[206:209], v[170:173], v[92:95]
	v_mfma_f32_16x16x32_bf16 v[88:91], v[214:217], v[170:173], v[88:91]
	v_mfma_f32_16x16x32_bf16 v[76:79], v[206:209], v[190:193], v[76:79]
	v_mfma_f32_16x16x32_bf16 v[72:75], v[214:217], v[190:193], v[72:75]
	v_mfma_f32_16x16x32_bf16 v[68:71], v[206:209], v[198:201], v[68:71]
	v_mfma_f32_16x16x32_bf16 v[64:67], v[214:217], v[198:201], v[64:67]
	s_setprio 0
	s_mov_b32 m0, s28
	s_barrier
	ds_read_b128 v[158:161], v141 offset:49152
	ds_read_b128 v[162:165], v141 offset:50176
	ds_read_b128 v[166:169], v141 offset:51200
	ds_read_b128 v[170:173], v141 offset:52224
	ds_read_b128 v[182:185], v141 offset:53248
	ds_read_b128 v[190:193], v141 offset:54272
	ds_read_b128 v[194:197], v141 offset:55296
	ds_read_b128 v[198:201], v141 offset:56320
	global_load_lds_dwordx4 v132, s[100:101]
	s_mov_b32 m0, s29
	s_nop 0
	global_load_lds_dwordx4 v130, s[100:101]
	s_barrier
; #define PG8_STAGE(bufoff, gbase, voff) do { _Pragma("unroll") for (int _i = 0; _i < 2; ++_i) \
;         __builtin_amdgcn_global_load_lds((const unsigned*)((const char*)(gbase) + (voff)[_i]), (PG8_LAS unsigned*)(lds + (bufoff) + ldsw + _i * 8192), 16, 0, 0); } while (0)
; #define PG8_MMA(ai, bj, At, Bt) do { __builtin_amdgcn_s_setprio(1); _Pragma("unroll") for (int m = 0; m < 4; ++m) _Pragma("unroll") for (int n = 0; n < 2; ++n) _Pragma("unroll") for (int k = 0; k < 2; ++k) \
;         acc[ai][bj][m][n] = __builtin_amdgcn_mfma_f32_16x16x32_bf16(Bt[n][k], At[m][k], acc[ai][bj][m][n], 0, 0, 0); __builtin_amdgcn_s_setprio(0); } while (0)
; #define PG8_WAIT_V(n) asm volatile("s_waitcnt vmcnt(" #n ")" ::: "memory")
; #define PG8_WAIT_L(n) asm volatile("s_waitcnt lgkmcnt(" #n ")" ::: "memory")
; #define PG8_BAR __builtin_amdgcn_s_barrier()
; #define PG8_SCHED __builtin_amdgcn_sched_barrier(0)
; template <class Epi, class Sched>
; __device__ __forceinline__ void gemm_phase(PG8_LAS unsigned char* lds, const Gemm g, const Sched& S, const Epi& E) {
;     ...
;             PG8_BAR; PG8_WAIT_L(0); PG8_MMA(1, 0, At, B0); PG8_BAR; PG8_SCHED;
;             PG8_STAGE(PG8_SB(1, 1), b3 + hstep, voffB);
;             PG8_WAIT_V(6); PG8_BAR; PG8_MMA(1, 1, At, B1); PG8_BAR;
;         }
	s_waitcnt lgkmcnt(0)
	s_setprio 1
	v_mfma_f32_16x16x32_bf16 v[60:63], v[142:145], v[158:161], v[60:63]
	v_mfma_f32_16x16x32_bf16 v[56:59], v[150:153], v[158:161], v[56:59]
	v_mfma_f32_16x16x32_bf16 v[52:55], v[142:145], v[166:169], v[52:55]
	v_mfma_f32_16x16x32_bf16 v[48:51], v[150:153], v[166:169], v[48:51]
	v_mfma_f32_16x16x32_bf16 v[36:39], v[142:145], v[182:185], v[36:39]
	v_mfma_f32_16x16x32_bf16 v[32:35], v[150:153], v[182:185], v[32:35]
	v_mfma_f32_16x16x32_bf16 v[20:23], v[142:145], v[194:197], v[20:23]
	v_mfma_f32_16x16x32_bf16 v[16:19], v[150:153], v[194:197], v[16:19]
	v_mfma_f32_16x16x32_bf16 v[60:63], v[146:149], v[162:165], v[60:63]
	v_mfma_f32_16x16x32_bf16 v[56:59], v[154:157], v[162:165], v[56:59]
	v_mfma_f32_16x16x32_bf16 v[52:55], v[146:149], v[170:173], v[52:55]
	v_mfma_f32_16x16x32_bf16 v[48:51], v[154:157], v[170:173], v[48:51]
	v_mfma_f32_16x16x32_bf16 v[36:39], v[146:149], v[190:193], v[36:39]
	v_mfma_f32_16x16x32_bf16 v[32:35], v[154:157], v[190:193], v[32:35]
	v_mfma_f32_16x16x32_bf16 v[20:23], v[146:149], v[198:201], v[20:23]
	v_mfma_f32_16x16x32_bf16 v[16:19], v[154:157], v[198:201], v[16:19]
	s_setprio 0
	s_barrier
	s_add_u32 s14, s14, 0x40080
	s_addc_u32 s15, s15, 0
	s_add_i32 s16, s16, s20
	s_mov_b32 m0, s16
	s_nop 0
	global_load_lds_dwordx4 v176, s[14:15]
	s_add_i32 m0, s16, 0x2000
	s_nop 0
	global_load_lds_dwordx4 v128, s[14:15]
	s_waitcnt vmcnt(6)
	s_barrier
	s_setprio 1
	v_mfma_f32_16x16x32_bf16 v[44:47], v[202:205], v[158:161], v[44:47]
	v_mfma_f32_16x16x32_bf16 v[40:43], v[210:213], v[158:161], v[40:43]
	v_mfma_f32_16x16x32_bf16 v[28:31], v[202:205], v[166:169], v[28:31]
	v_mfma_f32_16x16x32_bf16 v[24:27], v[210:213], v[166:169], v[24:27]
	v_mfma_f32_16x16x32_bf16 v[12:15], v[202:205], v[182:185], v[12:15]
	v_mfma_f32_16x16x32_bf16 v[8:11], v[210:213], v[182:185], v[8:11]
	v_mfma_f32_16x16x32_bf16 v[4:7], v[202:205], v[194:197], v[4:7]
	v_mfma_f32_16x16x32_bf16 v[0:3], v[210:213], v[194:197], v[0:3]
	v_mfma_f32_16x16x32_bf16 v[44:47], v[206:209], v[162:165], v[44:47]
	v_mfma_f32_16x16x32_bf16 v[40:43], v[214:217], v[162:165], v[40:43]
	v_mfma_f32_16x16x32_bf16 v[28:31], v[206:209], v[170:173], v[28:31]
	v_mfma_f32_16x16x32_bf16 v[24:27], v[214:217], v[170:173], v[24:27]
	v_mfma_f32_16x16x32_bf16 v[12:15], v[206:209], v[190:193], v[12:15]
	v_mfma_f32_16x16x32_bf16 v[8:11], v[214:217], v[190:193], v[8:11]
	v_mfma_f32_16x16x32_bf16 v[4:7], v[206:209], v[198:201], v[4:7]
	v_mfma_f32_16x16x32_bf16 v[0:3], v[214:217], v[198:201], v[0:3]
	s_setprio 0
	s_add_i32 s45, s45, 2
	s_add_u32 s12, s12, 0x100
	s_addc_u32 s13, s13, 0
	s_add_u32 s43, s43, 0x100
	s_addc_u32 s44, s44, 0
	s_cmp_gt_u32 s45, 13
	s_barrier
	s_cbranch_scc0 .LBB0_358
; __device__ __forceinline__ unsigned cvtpk(float lo, float hi) { const f32x2 v = (f32x2){lo, hi}; const bf16v2 b = __builtin_convertvector(v, bf16v2); return __builtin_bit_cast(unsigned, b); }
; #define PG8_WAIT_V(n) asm volatile("s_waitcnt vmcnt(" #n ")" ::: "memory")
; #define PG8_BAR __builtin_amdgcn_s_barrier()
; template <class Epi, class Sched>
; __device__ __forceinline__ void gemm_phase(PG8_LAS unsigned char* lds, const Gemm g, const Sched& S, const Epi& E) {
;     ...
;         if constexpr (!Epi::AFTER_DRAIN) { E(acc, cur, wr, wc, fr, fq); S.done(cur); }
;         if (!has_next) break;
; #pragma unroll
;         for (int a = 0; a < 2; ++a)
; #pragma unroll
;             for (int b = 0; b < 2; ++b)
; #pragma unroll
;                 for (int m = 0; m < 4; ++m)
; #pragma unroll
;                     for (int n = 0; n < 2; ++n) acc[a][b][m][n] = (f32x4){0.f, 0.f, 0.f, 0.f};
;         cur = nxt; cA = nA; cB = nB; ++ui;
;     }
;     PG8_WAIT_V(0);
;     if (wr == 0) PG8_BAR;
;     __device__ __forceinline__ void operator()(const f32x4 (&acc)[2][2][4][2], const pg8::Unit& u, int wr, int wc, int fr, int fq) const {
;         const int row0 = u.pm * 256 + wr * 64 + fr, col0 = u.pn * 256 + wc * 32 + 8 * fq;
; #pragma unroll
;         for (int ai = 0; ai < 2; ++ai)
; #pragma unroll
;             for (int m = 0; m < 4; ++m) { bf16_t* rowp = O + (size_t)(row0 + ai * 128 + m * 16) * ldc + col0;
; #pragma unroll
;                 for (int bj = 0; bj < 2; ++bj) { const f32x4 v0 = acc[ai][bj][m][0], v1 = acc[ai][bj][m][1];
;                     u32x4 w; w.x = cvtpk(v0[0], v0[1]); w.y = cvtpk(v0[2], v0[3]); w.z = cvtpk(v1[0], v1[1]); w.w = cvtpk(v1[2], v1[3]);
;                     *(u32x4*)(rowp + bj * 128) = w; } }
	v_readlane_b32 s12, v253, 16
	v_lshl_add_u32 v148, s0, 8, v138
	v_lshl_or_b32 v142, s34, 8, v140
	v_readlane_b32 s13, v253, 17
	v_ashrrev_i32_e32 v143, 31, v142
	v_cvt_pk_bf16_f32 v68, v68, v69
	v_mov_b64_e32 v[144:145], s[12:13]
	v_cvt_pk_bf16_f32 v69, v70, v71
	v_cvt_pk_bf16_f32 v70, v64, v65
	v_add_u32_e32 v64, 0x80, v148
	v_mad_i64_i32 v[146:147], s[12:13], v148, s81, v[144:145]
	v_lshlrev_b64 v[142:143], 1, v[142:143]
	v_cvt_pk_bf16_f32 v108, v108, v109
	v_cvt_pk_bf16_f32 v109, v110, v111
	v_cvt_pk_bf16_f32 v110, v104, v105
	v_or_b32_e32 v104, 16, v148
	v_mad_i64_i32 v[64:65], s[12:13], v64, s81, v[144:145]
	v_cvt_pk_bf16_f32 v44, v44, v45
	v_cvt_pk_bf16_f32 v45, v46, v47
	v_cvt_pk_bf16_f32 v46, v40, v41
	v_add_u32_e32 v40, 0x90, v148
	v_lshl_add_u64 v[146:147], v[146:147], 0, v[142:143]
	v_cvt_pk_bf16_f32 v111, v106, v107
	v_mad_i64_i32 v[104:105], s[12:13], v104, s81, v[144:145]
	v_cvt_pk_bf16_f32 v92, v92, v93
	v_cvt_pk_bf16_f32 v93, v94, v95
	v_cvt_pk_bf16_f32 v94, v88, v89
	v_or_b32_e32 v88, 32, v148
	v_lshl_add_u64 v[64:65], v[64:65], 0, v[142:143]
	v_cvt_pk_bf16_f32 v47, v42, v43
	v_mad_i64_i32 v[40:41], s[12:13], v40, s81, v[144:145]
	v_cvt_pk_bf16_f32 v28, v28, v29
	v_cvt_pk_bf16_f32 v29, v30, v31
	v_cvt_pk_bf16_f32 v30, v24, v25
	v_add_u32_e32 v24, 0xa0, v148
	global_store_dwordx4 v[146:147], v[108:111], off offset:256
	v_cvt_pk_bf16_f32 v95, v90, v91
	v_mad_i64_i32 v[88:89], s[12:13], v88, s81, v[144:145]
	v_lshl_add_u64 v[108:109], v[104:105], 0, v[142:143]
	v_cvt_pk_bf16_f32 v76, v76, v77
	v_cvt_pk_bf16_f32 v77, v78, v79
	v_cvt_pk_bf16_f32 v78, v72, v73
	v_or_b32_e32 v72, 48, v148
	global_store_dwordx4 v[64:65], v[44:47], off offset:256
	v_cvt_pk_bf16_f32 v31, v26, v27
	v_mad_i64_i32 v[24:25], s[12:13], v24, s81, v[144:145]
	v_lshl_add_u64 v[44:45], v[40:41], 0, v[142:143]
	v_cvt_pk_bf16_f32 v12, v12, v13
	v_cvt_pk_bf16_f32 v13, v14, v15
	v_cvt_pk_bf16_f32 v14, v8, v9
	v_add_u32_e32 v8, 0xb0, v148
	global_store_dwordx4 v[108:109], v[92:95], off offset:256
	v_cvt_pk_bf16_f32 v79, v74, v75
	v_mad_i64_i32 v[72:73], s[12:13], v72, s81, v[144:145]
	v_lshl_add_u64 v[92:93], v[88:89], 0, v[142:143]
	global_store_dwordx4 v[44:45], v[28:31], off offset:256
	v_cvt_pk_bf16_f32 v15, v10, v11
	v_mad_i64_i32 v[8:9], s[12:13], v8, s81, v[144:145]
	v_lshl_add_u64 v[28:29], v[24:25], 0, v[142:143]
	v_cvt_pk_bf16_f32 v124, v124, v125
	v_cvt_pk_bf16_f32 v125, v126, v127
	v_cvt_pk_bf16_f32 v126, v120, v121
	v_cvt_pk_bf16_f32 v127, v122, v123
	v_cvt_pk_bf16_f32 v104, v116, v117
	v_cvt_pk_bf16_f32 v105, v118, v119
	v_cvt_pk_bf16_f32 v106, v112, v113
	v_cvt_pk_bf16_f32 v107, v114, v115
	v_cvt_pk_bf16_f32 v88, v100, v101
	v_cvt_pk_bf16_f32 v89, v102, v103
	v_cvt_pk_bf16_f32 v90, v96, v97
	v_cvt_pk_bf16_f32 v91, v98, v99
	global_store_dwordx4 v[92:93], v[76:79], off offset:256
	v_cvt_pk_bf16_f32 v74, v80, v81
	v_cvt_pk_bf16_f32 v75, v82, v83
	v_lshl_add_u64 v[76:77], v[72:73], 0, v[142:143]
	v_cvt_pk_bf16_f32 v72, v84, v85
	v_cvt_pk_bf16_f32 v73, v86, v87
	v_cvt_pk_bf16_f32 v71, v66, v67
	v_cvt_pk_bf16_f32 v60, v60, v61
	v_cvt_pk_bf16_f32 v61, v62, v63
	v_cvt_pk_bf16_f32 v62, v56, v57
	v_cvt_pk_bf16_f32 v63, v58, v59
	v_cvt_pk_bf16_f32 v40, v52, v53
	v_cvt_pk_bf16_f32 v41, v54, v55
	v_cvt_pk_bf16_f32 v42, v48, v49
	v_cvt_pk_bf16_f32 v43, v50, v51
	v_cvt_pk_bf16_f32 v24, v36, v37
	v_cvt_pk_bf16_f32 v25, v38, v39
	v_cvt_pk_bf16_f32 v26, v32, v33
	v_cvt_pk_bf16_f32 v27, v34, v35
	global_store_dwordx4 v[28:29], v[12:15], off offset:256
	v_cvt_pk_bf16_f32 v10, v16, v17
	v_cvt_pk_bf16_f32 v11, v18, v19
	v_lshl_add_u64 v[12:13], v[8:9], 0, v[142:143]
	v_cvt_pk_bf16_f32 v8, v20, v21
	v_cvt_pk_bf16_f32 v9, v22, v23
	v_cvt_pk_bf16_f32 v4, v4, v5
	v_cvt_pk_bf16_f32 v5, v6, v7
	v_cvt_pk_bf16_f32 v6, v0, v1
	v_cvt_pk_bf16_f32 v7, v2, v3
	s_and_b64 vcc, exec, s[38:39]
	s_mov_b32 s34, s4
	s_mov_b32 s0, s6
	s_mov_b64 s[14:15], s[10:11]
	s_mov_b64 s[12:13], s[8:9]
	global_store_dwordx4 v[146:147], v[124:127], off
	global_store_dwordx4 v[108:109], v[104:107], off
	global_store_dwordx4 v[92:93], v[88:91], off
	global_store_dwordx4 v[76:77], v[72:75], off
	global_store_dwordx4 v[76:77], v[68:71], off offset:256
	global_store_dwordx4 v[64:65], v[60:63], off
	global_store_dwordx4 v[44:45], v[40:43], off
	global_store_dwordx4 v[28:29], v[24:27], off
	global_store_dwordx4 v[12:13], v[8:11], off
	global_store_dwordx4 v[12:13], v[4:7], off offset:256
	s_cbranch_vccz .LBB0_355
	s_waitcnt vmcnt(0)
	v_readlane_b32 s22, v255, 14
	s_cmpk_gt_u32 s19, 0xff
	v_readlane_b32 s23, v255, 15
	s_mov_b64 s[28:29], s[54:55]
	s_cbranch_scc1 .LBB0_362
	s_barrier

; __global__ void __launch_bounds__(NTHR, 2) mk_fwd(Params p) {
	.amdhsa_kernel _Z6mk_fwd6Params
		.amdhsa_group_segment_fixed_size 0
		.amdhsa_private_segment_fixed_size 0
		.amdhsa_kernarg_size 448
		.amdhsa_user_sgpr_count 2
		.amdhsa_user_sgpr_dispatch_ptr 0
		.amdhsa_user_sgpr_queue_ptr 0
		.amdhsa_user_sgpr_kernarg_segment_ptr 1
		.amdhsa_user_sgpr_dispatch_id 0
		.amdhsa_user_sgpr_kernarg_preload_length 0
		.amdhsa_user_sgpr_kernarg_preload_offset 0
		.amdhsa_user_sgpr_private_segment_size 0
		.amdhsa_uses_dynamic_stack 0
		.amdhsa_enable_private_segment 0
		.amdhsa_system_sgpr_workgroup_id_x 1
		.amdhsa_system_sgpr_workgroup_id_y 0
		.amdhsa_system_sgpr_workgroup_id_z 0
		.amdhsa_system_sgpr_workgroup_info 0
		.amdhsa_system_vgpr_workitem_id 2
		.amdhsa_next_free_vgpr 256
		.amdhsa_next_free_sgpr 102
		.amdhsa_accum_offset 256
		.amdhsa_reserve_vcc 1
		.amdhsa_float_round_mode_32 0
		.amdhsa_float_round_mode_16_64 0
		.amdhsa_float_denorm_mode_32 3
		.amdhsa_float_denorm_mode_16_64 3
		.amdhsa_dx10_clamp 1
		.amdhsa_ieee_mode 1
		.amdhsa_fp16_overflow 0
		.amdhsa_tg_split 0
		.amdhsa_exception_fp_ieee_invalid_op 0
		.amdhsa_exception_fp_denorm_src 0
		.amdhsa_exception_fp_ieee_div_zero 0
		.amdhsa_exception_fp_ieee_overflow 0
		.amdhsa_exception_fp_ieee_underflow 0
		.amdhsa_exception_fp_ieee_inexact 0
		.amdhsa_exception_int_div_zero 0
	.end_amdhsa_kernel

; __global__ void __launch_bounds__(NTHR, 2) mk_fwd(Params p) {
amdhsa.kernels:
  - .agpr_count:     0
    .args:
      - .offset:         0
        .size:           192
        .value_kind:     by_value
      - .offset:         192
        .size:           4
        .value_kind:     hidden_block_count_x
      - .offset:         196
        .size:           4
        .value_kind:     hidden_block_count_y
      - .offset:         200
        .size:           4
        .value_kind:     hidden_block_count_z
      - .offset:         204
        .size:           2
        .value_kind:     hidden_group_size_x
      - .offset:         206
        .size:           2
        .value_kind:     hidden_group_size_y
      - .offset:         208
        .size:           2
        .value_kind:     hidden_group_size_z
      - .offset:         210
        .size:           2
        .value_kind:     hidden_remainder_x
      - .offset:         212
        .size:           2
        .value_kind:     hidden_remainder_y
      - .offset:         214
        .size:           2
        .value_kind:     hidden_remainder_z
      - .offset:         232
        .size:           8
        .value_kind:     hidden_global_offset_x
      - .offset:         240
        .size:           8
        .value_kind:     hidden_global_offset_y
      - .offset:         248
        .size:           8
        .value_kind:     hidden_global_offset_z
      - .offset:         256
        .size:           2
        .value_kind:     hidden_grid_dims
      - .offset:         280
        .size:           8
        .value_kind:     hidden_multigrid_sync_arg
      - .offset:         312
        .size:           4
        .value_kind:     hidden_dynamic_lds_size
    .group_segment_fixed_size: 0
    .kernarg_segment_align: 8
    .kernarg_segment_size: 448
    .language:       OpenCL C
    .language_version:
      - 2
      - 0
    .max_flat_workgroup_size: 512
    .name:           _Z6mk_fwd6Params
    .private_segment_fixed_size: 0
    .sgpr_count:     108
    .sgpr_spill_count: 178
    .symbol:         _Z6mk_fwd6Params.kd
    .uniform_work_group_size: 1
    .uses_dynamic_stack: false
    .vgpr_count:     256
    .vgpr_spill_count: 0
    .wavefront_size: 64
